# GEMM K-loops: peeled first iteration with srcC=0 MFMAs, removed 128 accumulator-zeroing v_movs per tile
# baseline (speedup 1.0000x reference)
; #define PG8_STAGE(bufoff, gbase, voff) do { _Pragma("unroll") for (int _i = 0; _i < 2; ++_i) \
;         __builtin_amdgcn_global_load_lds((const unsigned*)((const char*)(gbase) + (voff)[_i]), (LAS unsigned*)(lds + (bufoff) + ldsw + _i * 8192), 16, 0, 0); } while (0)
; #define PG8_LDA(dst, b, h) do { _Pragma("unroll") for (int m = 0; m < 4; ++m) _Pragma("unroll") for (int k = 0; k < 2; ++k) dst[m][k] = *(const LAS bf16x8*)(lds + PG8_SA(b, h) + aoff + m * 2048 + k * 1024); } while (0)
; #define PG8_LDB(dst, b, h) do { _Pragma("unroll") for (int n = 0; n < 2; ++n) _Pragma("unroll") for (int k = 0; k < 2; ++k) dst[n][k] = *(const LAS bf16x8*)(lds + PG8_SB(b, h) + boff + n * 2048 + k * 1024); } while (0)
; #define PG8_MMA(ai, bj, At, Bt) do { __builtin_amdgcn_s_setprio(1); _Pragma("unroll") for (int m = 0; m < 4; ++m) _Pragma("unroll") for (int n = 0; n < 2; ++n) _Pragma("unroll") for (int k = 0; k < 2; ++k) \
;         acc[ai][bj][m][n] = __builtin_amdgcn_mfma_f32_16x16x32_bf16(Bt[n][k], At[m][k], acc[ai][bj][m][n], 0, 0, 0); __builtin_amdgcn_s_setprio(0); } while (0)
; #define PG8_WAIT_L(n) asm volatile("s_waitcnt lgkmcnt(" #n ")" ::: "memory")
; template <class Epi, class Sched>
; __device__ __forceinline__ void gemm_phase(LAS unsigned char* lds, const Gemm g, const Sched& S, const Epi& E, int tid) {
;     ...
;         const bool has_next = S.next(ui + 1, nxt);
;         const char* nA = has_next ? (const char*)g.A + (size_t)nxt.pm * tstep : cA; const char* nB = has_next ? (const char*)g.Bt + (size_t)nxt.pn * tstep : cB;
;         for (int t = 0; t < nt; t += 2) {
;             const bool last = (t == nt - 2);
;             const char* a1 = cA + (size_t)(t + 1) * kstep;
;             const char* a2 = last ? nA : cA + (size_t)(t + 2) * kstep; const char* b2 = last ? nB : cB + (size_t)(t + 2) * kstep;
;             const char* a3 = a2 + kstep; const char* b3 = b2 + kstep;
;             PG8_LDB(B0, 0, 0); PG8_SCHED; PG8_LDA(At, 0, 0); PG8_STAGE(PG8_SA(1, 1), a1 + hstep, voffA);
;             PG8_WAIT_L(8); PG8_BAR; PG8_WAIT_L(0); PG8_MMA(0, 0, At, B0); PG8_BAR; PG8_SCHED;
;             PG8_LDB(B1, 0, 1); PG8_STAGE(PG8_SB(0, 0), b2, voffB);
;             PG8_BAR; PG8_WAIT_L(0); PG8_MMA(0, 1, At, B1); PG8_BAR;
;             PG8_LDA(At, 0, 1); PG8_STAGE(PG8_SA(0, 0), a2, voffA);
;             PG8_BAR; PG8_WAIT_L(0); PG8_MMA(1, 0, At, B0); PG8_BAR; PG8_SCHED;
.LBB0_99:
	s_add_u32 vcc_lo, s44, 0x80
	s_addc_u32 vcc_hi, s45, 0
	s_add_u32 s96, s34, 0x100
	s_addc_u32 s65, s35, 0
	s_mov_b32 s34, 0
	s_waitcnt vmcnt(0)
	s_add_i32 s0, s34, 2
	s_add_u32 s1, vcc_lo, 0x80
	s_addc_u32 s35, vcc_hi, 0
	s_add_i32 s17, 0, 0x10000
	v_add_u32_e32 v152, s17, v141
	ds_read_b128 v[144:147], v152
	ds_read_b128 v[148:151], v152 offset:1024
	ds_read_b128 v[160:163], v152 offset:2048
	ds_read_b128 v[164:167], v152 offset:3072
	s_cmp_eq_u32 s95, s34
	s_cselect_b32 s34, s38, s1
	s_cselect_b32 s35, s39, s35
	s_cselect_b32 s45, s41, s65
	s_cselect_b32 s44, s40, s96
	v_lshl_add_u64 v[152:153], vcc, 0, v[134:135]
	s_add_i32 m0, s88, 0xc000
	ds_read_b128 v[168:171], v143
	ds_read_b128 v[184:187], v143 offset:1024
	ds_read_b128 v[188:191], v143 offset:2048
	ds_read_b128 v[192:195], v143 offset:3072
	ds_read_b128 v[196:199], v143 offset:4096
	ds_read_b128 v[200:203], v143 offset:5120
	ds_read_b128 v[204:207], v143 offset:6144
	ds_read_b128 v[208:211], v143 offset:7168
	global_load_lds_dwordx4 v[152:153], off
	v_lshl_add_u64 v[152:153], vcc, 0, v[136:137]
	s_add_i32 m0, s88, 0xe000
	s_nop 0
	global_load_lds_dwordx4 v[152:153], off
	s_waitcnt lgkmcnt(8)
	s_barrier
	s_waitcnt lgkmcnt(0)
	s_setprio 1
	s_waitcnt lgkmcnt(0)
	v_mfma_f32_16x16x32_bf16 v[124:127], v[144:147], v[168:171], 0
	v_mfma_f32_16x16x32_bf16 v[120:123], v[160:163], v[168:171], 0
	v_mfma_f32_16x16x32_bf16 v[116:119], v[144:147], v[188:191], 0
	v_mfma_f32_16x16x32_bf16 v[112:115], v[160:163], v[188:191], 0
	v_mfma_f32_16x16x32_bf16 v[100:103], v[144:147], v[196:199], 0
	v_mfma_f32_16x16x32_bf16 v[96:99], v[160:163], v[196:199], 0
	v_mfma_f32_16x16x32_bf16 v[84:87], v[144:147], v[204:207], 0
	v_mfma_f32_16x16x32_bf16 v[80:83], v[160:163], v[204:207], 0
	v_mfma_f32_16x16x32_bf16 v[124:127], v[148:151], v[184:187], v[124:127]
	v_mfma_f32_16x16x32_bf16 v[120:123], v[164:167], v[184:187], v[120:123]
	v_mfma_f32_16x16x32_bf16 v[116:119], v[148:151], v[192:195], v[116:119]
	v_mfma_f32_16x16x32_bf16 v[112:115], v[164:167], v[192:195], v[112:115]
	v_mfma_f32_16x16x32_bf16 v[100:103], v[148:151], v[200:203], v[100:103]
	v_mfma_f32_16x16x32_bf16 v[96:99], v[164:167], v[200:203], v[96:99]
	v_mfma_f32_16x16x32_bf16 v[84:87], v[148:151], v[208:211], v[84:87]
	v_mfma_f32_16x16x32_bf16 v[80:83], v[164:167], v[208:211], v[80:83]
	s_setprio 0
	s_barrier
	s_add_i32 s1, 0, 0x14000
	v_add_u32_e32 v152, s1, v141
	s_add_i32 s17, s17, s85
	ds_read_b128 v[212:215], v152
	ds_read_b128 v[216:219], v152 offset:1024
	ds_read_b128 v[220:223], v152 offset:2048
	ds_read_b128 v[224:227], v152 offset:3072
	v_lshl_add_u64 v[152:153], s[44:45], 0, v[154:155]
	s_mov_b32 m0, s17
	v_lshl_add_u64 v[228:229], s[44:45], 0, v[132:133]
	global_load_lds_dwordx4 v[152:153], off
	s_add_i32 m0, s17, 0x2000
	s_nop 0
	global_load_lds_dwordx4 v[228:229], off
	s_barrier
	s_waitcnt lgkmcnt(0)
	s_setprio 1
	s_waitcnt lgkmcnt(0)
	v_mfma_f32_16x16x32_bf16 v[108:111], v[212:215], v[168:171], 0
	v_mfma_f32_16x16x32_bf16 v[104:107], v[220:223], v[168:171], 0
	v_mfma_f32_16x16x32_bf16 v[92:95], v[212:215], v[188:191], 0
	v_mfma_f32_16x16x32_bf16 v[88:91], v[220:223], v[188:191], 0
	v_mfma_f32_16x16x32_bf16 v[76:79], v[212:215], v[196:199], 0
	v_mfma_f32_16x16x32_bf16 v[72:75], v[220:223], v[196:199], 0
	v_mfma_f32_16x16x32_bf16 v[68:71], v[212:215], v[204:207], 0
	v_mfma_f32_16x16x32_bf16 v[64:67], v[220:223], v[204:207], 0
	v_mfma_f32_16x16x32_bf16 v[108:111], v[216:219], v[184:187], v[108:111]
	v_mfma_f32_16x16x32_bf16 v[104:107], v[224:227], v[184:187], v[104:107]
	v_mfma_f32_16x16x32_bf16 v[92:95], v[216:219], v[192:195], v[92:95]
	v_mfma_f32_16x16x32_bf16 v[88:91], v[224:227], v[192:195], v[88:91]
	v_mfma_f32_16x16x32_bf16 v[76:79], v[216:219], v[200:203], v[76:79]
	v_mfma_f32_16x16x32_bf16 v[72:75], v[224:227], v[200:203], v[72:75]
	v_mfma_f32_16x16x32_bf16 v[68:71], v[216:219], v[208:211], v[68:71]
	v_mfma_f32_16x16x32_bf16 v[64:67], v[224:227], v[208:211], v[64:67]
	s_setprio 0
	s_mov_b32 m0, s88
	v_lshl_add_u64 v[230:231], s[34:35], 0, v[128:129]
	s_barrier
	ds_read_b128 v[168:171], v143 offset:16384
	ds_read_b128 v[184:187], v143 offset:17408
	ds_read_b128 v[188:191], v143 offset:18432
	ds_read_b128 v[192:195], v143 offset:19456
	ds_read_b128 v[196:199], v143 offset:20480
	ds_read_b128 v[200:203], v143 offset:21504
	ds_read_b128 v[204:207], v143 offset:22528
	ds_read_b128 v[208:211], v143 offset:23552
	global_load_lds_dwordx4 v[230:231], off
	v_lshl_add_u64 v[232:233], s[34:35], 0, v[130:131]
	s_mov_b32 m0, s89
	s_nop 0
	global_load_lds_dwordx4 v[232:233], off
	s_barrier
	s_waitcnt lgkmcnt(0)
	s_setprio 1
	s_waitcnt lgkmcnt(0)
	v_mfma_f32_16x16x32_bf16 v[60:63], v[144:147], v[168:171], 0
	v_mfma_f32_16x16x32_bf16 v[56:59], v[160:163], v[168:171], 0
	v_mfma_f32_16x16x32_bf16 v[52:55], v[144:147], v[188:191], 0
	v_mfma_f32_16x16x32_bf16 v[48:51], v[160:163], v[188:191], 0
	v_mfma_f32_16x16x32_bf16 v[36:39], v[144:147], v[196:199], 0
	v_mfma_f32_16x16x32_bf16 v[32:35], v[160:163], v[196:199], 0
	v_mfma_f32_16x16x32_bf16 v[20:23], v[144:147], v[204:207], 0
	v_mfma_f32_16x16x32_bf16 v[16:19], v[160:163], v[204:207], 0
	v_mfma_f32_16x16x32_bf16 v[60:63], v[148:151], v[184:187], v[60:63]
	v_mfma_f32_16x16x32_bf16 v[56:59], v[164:167], v[184:187], v[56:59]
	v_mfma_f32_16x16x32_bf16 v[52:55], v[148:151], v[192:195], v[52:55]
	v_mfma_f32_16x16x32_bf16 v[48:51], v[164:167], v[192:195], v[48:51]
	v_mfma_f32_16x16x32_bf16 v[36:39], v[148:151], v[200:203], v[36:39]
	v_mfma_f32_16x16x32_bf16 v[32:35], v[164:167], v[200:203], v[32:35]
	v_mfma_f32_16x16x32_bf16 v[20:23], v[148:151], v[208:211], v[20:23]
	v_mfma_f32_16x16x32_bf16 v[16:19], v[164:167], v[208:211], v[16:19]
	s_setprio 0
	s_barrier
; #define PG8_STAGE(bufoff, gbase, voff) do { _Pragma("unroll") for (int _i = 0; _i < 2; ++_i) \
;         __builtin_amdgcn_global_load_lds((const unsigned*)((const char*)(gbase) + (voff)[_i]), (LAS unsigned*)(lds + (bufoff) + ldsw + _i * 8192), 16, 0, 0); } while (0)
; #define PG8_LDA(dst, b, h) do { _Pragma("unroll") for (int m = 0; m < 4; ++m) _Pragma("unroll") for (int k = 0; k < 2; ++k) dst[m][k] = *(const LAS bf16x8*)(lds + PG8_SA(b, h) + aoff + m * 2048 + k * 1024); } while (0)
; #define PG8_LDB(dst, b, h) do { _Pragma("unroll") for (int n = 0; n < 2; ++n) _Pragma("unroll") for (int k = 0; k < 2; ++k) dst[n][k] = *(const LAS bf16x8*)(lds + PG8_SB(b, h) + boff + n * 2048 + k * 1024); } while (0)
; #define PG8_MMA(ai, bj, At, Bt) do { __builtin_amdgcn_s_setprio(1); _Pragma("unroll") for (int m = 0; m < 4; ++m) _Pragma("unroll") for (int n = 0; n < 2; ++n) _Pragma("unroll") for (int k = 0; k < 2; ++k) \
;         acc[ai][bj][m][n] = __builtin_amdgcn_mfma_f32_16x16x32_bf16(Bt[n][k], At[m][k], acc[ai][bj][m][n], 0, 0, 0); __builtin_amdgcn_s_setprio(0); } while (0)
; #define PG8_WAIT_V(n) asm volatile("s_waitcnt vmcnt(" #n ")" ::: "memory")
; #define PG8_WAIT_L(n) asm volatile("s_waitcnt lgkmcnt(" #n ")" ::: "memory")
; #define PG8_BAR __builtin_amdgcn_s_barrier()
; #define PG8_SCHED __builtin_amdgcn_sched_barrier(0)
; template <class Epi, class Sched>
; __device__ __forceinline__ void gemm_phase(LAS unsigned char* lds, const Gemm g, const Sched& S, const Epi& E, int tid) {
;     ...
;             PG8_STAGE(PG8_SB(0, 1), b2 + hstep, voffB);
;             PG8_WAIT_V(6); PG8_BAR; PG8_MMA(1, 1, At, B1); PG8_BAR;
;             PG8_LDB(B0, 1, 0); PG8_SCHED; PG8_LDA(At, 1, 0); PG8_STAGE(PG8_SA(0, 1), a2 + hstep, voffA);
;             PG8_WAIT_L(8); PG8_BAR; PG8_WAIT_L(0); PG8_MMA(0, 0, At, B0); PG8_BAR; PG8_SCHED;
;             PG8_LDB(B1, 1, 1); PG8_STAGE(PG8_SB(1, 0), b3, voffB);
;             PG8_BAR; PG8_WAIT_L(0); PG8_MMA(0, 1, At, B1); PG8_BAR;
	s_add_u32 s44, s44, s6
	s_addc_u32 s45, s45, 0
	s_add_i32 s1, s1, s85
	v_lshl_add_u64 v[234:235], s[44:45], 0, v[154:155]
	s_mov_b32 m0, s1
	v_lshl_add_u64 v[236:237], s[44:45], 0, v[132:133]
	global_load_lds_dwordx4 v[234:235], off
	s_add_i32 m0, s1, 0x2000
	s_nop 0
	global_load_lds_dwordx4 v[236:237], off
	s_waitcnt vmcnt(6)
	s_barrier
	s_setprio 1
	v_mfma_f32_16x16x32_bf16 v[44:47], v[212:215], v[168:171], 0
	v_mfma_f32_16x16x32_bf16 v[40:43], v[220:223], v[168:171], 0
	v_mfma_f32_16x16x32_bf16 v[28:31], v[212:215], v[188:191], 0
	v_mfma_f32_16x16x32_bf16 v[24:27], v[220:223], v[188:191], 0
	v_mfma_f32_16x16x32_bf16 v[12:15], v[212:215], v[196:199], 0
	v_mfma_f32_16x16x32_bf16 v[8:11], v[220:223], v[196:199], 0
	v_mfma_f32_16x16x32_bf16 v[4:7], v[212:215], v[204:207], 0
	v_mfma_f32_16x16x32_bf16 v[0:3], v[220:223], v[204:207], 0
	v_mfma_f32_16x16x32_bf16 v[44:47], v[216:219], v[184:187], v[44:47]
	v_mfma_f32_16x16x32_bf16 v[40:43], v[224:227], v[184:187], v[40:43]
	v_mfma_f32_16x16x32_bf16 v[28:31], v[216:219], v[192:195], v[28:31]
	v_mfma_f32_16x16x32_bf16 v[24:27], v[224:227], v[192:195], v[24:27]
	v_mfma_f32_16x16x32_bf16 v[12:15], v[216:219], v[200:203], v[12:15]
	v_mfma_f32_16x16x32_bf16 v[8:11], v[224:227], v[200:203], v[8:11]
	v_mfma_f32_16x16x32_bf16 v[4:7], v[216:219], v[208:211], v[4:7]
	v_mfma_f32_16x16x32_bf16 v[0:3], v[224:227], v[208:211], v[0:3]
	s_setprio 0
	s_add_i32 s1, 0, 0x18000
	v_add_u32_e32 v164, s1, v141
	s_barrier
	ds_read_b128 v[144:147], v164
	ds_read_b128 v[148:151], v164 offset:1024
	ds_read_b128 v[160:163], v164 offset:2048
	ds_read_b128 v[164:167], v164 offset:3072
	s_add_u32 s34, s34, s6
	s_addc_u32 s35, s35, 0
	s_mov_b32 m0, s90
	v_lshl_add_u64 v[212:213], s[34:35], 0, v[128:129]
	ds_read_b128 v[168:171], v143 offset:32768
	ds_read_b128 v[184:187], v143 offset:33792
	ds_read_b128 v[188:191], v143 offset:34816
	ds_read_b128 v[192:195], v143 offset:35840
	ds_read_b128 v[196:199], v143 offset:36864
	ds_read_b128 v[200:203], v143 offset:37888
	ds_read_b128 v[204:207], v143 offset:38912
	ds_read_b128 v[208:211], v143 offset:39936
	global_load_lds_dwordx4 v[212:213], off
	v_lshl_add_u64 v[212:213], s[34:35], 0, v[130:131]
	s_mov_b32 m0, s91
	s_nop 0
	global_load_lds_dwordx4 v[212:213], off
	s_waitcnt lgkmcnt(8)
	s_barrier
	s_waitcnt lgkmcnt(0)
	s_setprio 1
	s_waitcnt lgkmcnt(0)
	v_mfma_f32_16x16x32_bf16 v[124:127], v[144:147], v[168:171], v[124:127]
	v_mfma_f32_16x16x32_bf16 v[120:123], v[160:163], v[168:171], v[120:123]
	v_mfma_f32_16x16x32_bf16 v[116:119], v[144:147], v[188:191], v[116:119]
	v_mfma_f32_16x16x32_bf16 v[112:115], v[160:163], v[188:191], v[112:115]
	v_mfma_f32_16x16x32_bf16 v[100:103], v[144:147], v[196:199], v[100:103]
	v_mfma_f32_16x16x32_bf16 v[96:99], v[160:163], v[196:199], v[96:99]
	v_mfma_f32_16x16x32_bf16 v[84:87], v[144:147], v[204:207], v[84:87]
	v_mfma_f32_16x16x32_bf16 v[80:83], v[160:163], v[204:207], v[80:83]
	v_mfma_f32_16x16x32_bf16 v[124:127], v[148:151], v[184:187], v[124:127]
	v_mfma_f32_16x16x32_bf16 v[120:123], v[164:167], v[184:187], v[120:123]
	v_mfma_f32_16x16x32_bf16 v[116:119], v[148:151], v[192:195], v[116:119]
	v_mfma_f32_16x16x32_bf16 v[112:115], v[164:167], v[192:195], v[112:115]
	v_mfma_f32_16x16x32_bf16 v[100:103], v[148:151], v[200:203], v[100:103]
	v_mfma_f32_16x16x32_bf16 v[96:99], v[164:167], v[200:203], v[96:99]
	v_mfma_f32_16x16x32_bf16 v[84:87], v[148:151], v[208:211], v[84:87]
	v_mfma_f32_16x16x32_bf16 v[80:83], v[164:167], v[208:211], v[80:83]
	s_setprio 0
	s_barrier
	s_add_i32 s17, 0, 0x1c000
	s_add_i32 s1, s1, s85
	v_add_u32_e32 v183, s17, v141
	v_lshl_add_u64 v[152:153], v[152:153], 0, s[8:9]
	s_mov_b32 m0, s1
	ds_read_b128 v[212:215], v183
	ds_read_b128 v[216:219], v183 offset:1024
	ds_read_b128 v[220:223], v183 offset:2048
	ds_read_b128 v[224:227], v183 offset:3072
	global_load_lds_dwordx4 v[152:153], off
	v_lshl_add_u64 v[152:153], v[228:229], 0, s[8:9]
	s_add_i32 m0, s1, 0x2000
	s_nop 0
	global_load_lds_dwordx4 v[152:153], off
	s_barrier
; #define PG8_STAGE(bufoff, gbase, voff) do { _Pragma("unroll") for (int _i = 0; _i < 2; ++_i) \
;         __builtin_amdgcn_global_load_lds((const unsigned*)((const char*)(gbase) + (voff)[_i]), (LAS unsigned*)(lds + (bufoff) + ldsw + _i * 8192), 16, 0, 0); } while (0)
; #define PG8_LDA(dst, b, h) do { _Pragma("unroll") for (int m = 0; m < 4; ++m) _Pragma("unroll") for (int k = 0; k < 2; ++k) dst[m][k] = *(const LAS bf16x8*)(lds + PG8_SA(b, h) + aoff + m * 2048 + k * 1024); } while (0)
; #define PG8_MMA(ai, bj, At, Bt) do { __builtin_amdgcn_s_setprio(1); _Pragma("unroll") for (int m = 0; m < 4; ++m) _Pragma("unroll") for (int n = 0; n < 2; ++n) _Pragma("unroll") for (int k = 0; k < 2; ++k) \
;         acc[ai][bj][m][n] = __builtin_amdgcn_mfma_f32_16x16x32_bf16(Bt[n][k], At[m][k], acc[ai][bj][m][n], 0, 0, 0); __builtin_amdgcn_s_setprio(0); } while (0)
; #define PG8_WAIT_V(n) asm volatile("s_waitcnt vmcnt(" #n ")" ::: "memory")
; #define PG8_WAIT_L(n) asm volatile("s_waitcnt lgkmcnt(" #n ")" ::: "memory")
; #define PG8_BAR __builtin_amdgcn_s_barrier()
; #define PG8_SCHED __builtin_amdgcn_sched_barrier(0)
; template <class Epi, class Sched>
; __device__ __forceinline__ void gemm_phase(LAS unsigned char* lds, const Gemm g, const Sched& S, const Epi& E, int tid) {
;     ...
;             PG8_BAR; PG8_WAIT_L(0); PG8_MMA(0, 1, At, B1); PG8_BAR;
;             PG8_LDA(At, 1, 1); PG8_STAGE(PG8_SA(1, 0), a3, voffA);
;             PG8_BAR; PG8_WAIT_L(0); PG8_MMA(1, 0, At, B0); PG8_BAR; PG8_SCHED;
;             PG8_STAGE(PG8_SB(1, 1), b3 + hstep, voffB);
;             PG8_WAIT_V(6); PG8_BAR; PG8_MMA(1, 1, At, B1); PG8_BAR;
	s_waitcnt lgkmcnt(0)
	s_setprio 1
	s_waitcnt lgkmcnt(0)
	v_mfma_f32_16x16x32_bf16 v[108:111], v[212:215], v[168:171], v[108:111]
	v_mfma_f32_16x16x32_bf16 v[104:107], v[220:223], v[168:171], v[104:107]
	v_mfma_f32_16x16x32_bf16 v[92:95], v[212:215], v[188:191], v[92:95]
	v_mfma_f32_16x16x32_bf16 v[88:91], v[220:223], v[188:191], v[88:91]
	v_mfma_f32_16x16x32_bf16 v[76:79], v[212:215], v[196:199], v[76:79]
	v_mfma_f32_16x16x32_bf16 v[72:75], v[220:223], v[196:199], v[72:75]
	v_mfma_f32_16x16x32_bf16 v[68:71], v[212:215], v[204:207], v[68:71]
	v_mfma_f32_16x16x32_bf16 v[64:67], v[220:223], v[204:207], v[64:67]
	v_mfma_f32_16x16x32_bf16 v[108:111], v[216:219], v[184:187], v[108:111]
	v_mfma_f32_16x16x32_bf16 v[104:107], v[224:227], v[184:187], v[104:107]
	v_mfma_f32_16x16x32_bf16 v[92:95], v[216:219], v[192:195], v[92:95]
	v_mfma_f32_16x16x32_bf16 v[88:91], v[224:227], v[192:195], v[88:91]
	v_mfma_f32_16x16x32_bf16 v[76:79], v[216:219], v[200:203], v[76:79]
	v_mfma_f32_16x16x32_bf16 v[72:75], v[224:227], v[200:203], v[72:75]
	v_mfma_f32_16x16x32_bf16 v[68:71], v[216:219], v[208:211], v[68:71]
	v_mfma_f32_16x16x32_bf16 v[64:67], v[224:227], v[208:211], v[64:67]
	s_setprio 0
	s_mov_b32 m0, s92
	v_lshl_add_u64 v[152:153], v[230:231], 0, s[8:9]
	s_barrier
	ds_read_b128 v[168:171], v143 offset:49152
	ds_read_b128 v[184:187], v143 offset:50176
	ds_read_b128 v[188:191], v143 offset:51200
	ds_read_b128 v[192:195], v143 offset:52224
	ds_read_b128 v[196:199], v143 offset:53248
	ds_read_b128 v[200:203], v143 offset:54272
	ds_read_b128 v[204:207], v143 offset:55296
	ds_read_b128 v[208:211], v143 offset:56320
	global_load_lds_dwordx4 v[152:153], off
	v_lshl_add_u64 v[152:153], v[232:233], 0, s[8:9]
	s_mov_b32 m0, s93
	s_nop 0
	global_load_lds_dwordx4 v[152:153], off
	s_barrier
	s_waitcnt lgkmcnt(0)
	s_setprio 1
	s_waitcnt lgkmcnt(0)
	v_mfma_f32_16x16x32_bf16 v[60:63], v[144:147], v[168:171], v[60:63]
	v_mfma_f32_16x16x32_bf16 v[56:59], v[160:163], v[168:171], v[56:59]
	v_mfma_f32_16x16x32_bf16 v[52:55], v[144:147], v[188:191], v[52:55]
	v_mfma_f32_16x16x32_bf16 v[48:51], v[160:163], v[188:191], v[48:51]
	v_mfma_f32_16x16x32_bf16 v[36:39], v[144:147], v[196:199], v[36:39]
	v_mfma_f32_16x16x32_bf16 v[32:35], v[160:163], v[196:199], v[32:35]
	v_mfma_f32_16x16x32_bf16 v[20:23], v[144:147], v[204:207], v[20:23]
	v_mfma_f32_16x16x32_bf16 v[16:19], v[160:163], v[204:207], v[16:19]
	v_mfma_f32_16x16x32_bf16 v[60:63], v[148:151], v[184:187], v[60:63]
	v_mfma_f32_16x16x32_bf16 v[56:59], v[164:167], v[184:187], v[56:59]
	v_mfma_f32_16x16x32_bf16 v[52:55], v[148:151], v[192:195], v[52:55]
	v_mfma_f32_16x16x32_bf16 v[48:51], v[164:167], v[192:195], v[48:51]
	v_mfma_f32_16x16x32_bf16 v[36:39], v[148:151], v[200:203], v[36:39]
	v_mfma_f32_16x16x32_bf16 v[32:35], v[164:167], v[200:203], v[32:35]
	v_mfma_f32_16x16x32_bf16 v[20:23], v[148:151], v[208:211], v[20:23]
	v_mfma_f32_16x16x32_bf16 v[16:19], v[164:167], v[208:211], v[16:19]
	s_setprio 0
	s_barrier
	s_add_i32 s1, s17, s85
	v_lshl_add_u64 v[144:145], v[234:235], 0, s[8:9]
	s_mov_b32 m0, s1
	s_nop 0
	global_load_lds_dwordx4 v[144:145], off
	v_lshl_add_u64 v[144:145], v[236:237], 0, s[8:9]
	s_add_i32 m0, s1, 0x2000
	s_nop 0
	global_load_lds_dwordx4 v[144:145], off
	s_waitcnt vmcnt(6)
	s_barrier
	s_setprio 1
	v_mfma_f32_16x16x32_bf16 v[44:47], v[212:215], v[168:171], v[44:47]
	v_mfma_f32_16x16x32_bf16 v[40:43], v[220:223], v[168:171], v[40:43]
	v_mfma_f32_16x16x32_bf16 v[28:31], v[212:215], v[188:191], v[28:31]
	v_mfma_f32_16x16x32_bf16 v[24:27], v[220:223], v[188:191], v[24:27]
	v_mfma_f32_16x16x32_bf16 v[12:15], v[212:215], v[196:199], v[12:15]
	v_mfma_f32_16x16x32_bf16 v[8:11], v[220:223], v[196:199], v[8:11]
	v_mfma_f32_16x16x32_bf16 v[4:7], v[212:215], v[204:207], v[4:7]
	v_mfma_f32_16x16x32_bf16 v[0:3], v[220:223], v[204:207], v[0:3]
	v_mfma_f32_16x16x32_bf16 v[44:47], v[216:219], v[184:187], v[44:47]
	v_mfma_f32_16x16x32_bf16 v[40:43], v[224:227], v[184:187], v[40:43]
	v_mfma_f32_16x16x32_bf16 v[28:31], v[216:219], v[192:195], v[28:31]
	v_mfma_f32_16x16x32_bf16 v[24:27], v[224:227], v[192:195], v[24:27]
	v_mfma_f32_16x16x32_bf16 v[12:15], v[216:219], v[200:203], v[12:15]
	v_mfma_f32_16x16x32_bf16 v[8:11], v[224:227], v[200:203], v[8:11]
	v_mfma_f32_16x16x32_bf16 v[4:7], v[216:219], v[208:211], v[4:7]
	v_mfma_f32_16x16x32_bf16 v[0:3], v[224:227], v[208:211], v[0:3]
	s_setprio 0
	s_add_u32 vcc_lo, vcc_lo, 0x100
	s_addc_u32 vcc_hi, vcc_hi, 0
	s_add_u32 s96, s96, 0x100
	s_addc_u32 s65, s65, 0
	s_cmp_ge_u32 s0, s94
	s_mov_b32 s34, s0
	s_barrier
	s_cbranch_scc1 .Lpeel_exit_plain

; #define PG8_WAIT_V(n) asm volatile("s_waitcnt vmcnt(" #n ")" ::: "memory")
; #define PG8_BAR __builtin_amdgcn_s_barrier()
;     __device__ __forceinline__ void operator()(const f32x4 (&acc)[2][2][4][2], const Unit& u, int wr, int wc, int fr, int fq) const {
;         const int row0 = u.pm * BM + wr * 64 + fr, col0 = u.pn * BM + wc * 32 + 8 * fq;
; #pragma unroll
;         for (int ai = 0; ai < 2; ++ai)
; #pragma unroll
;             for (int m = 0; m < 4; ++m) { bf16_t* rowp = O + (size_t)(row0 + ai * HALF + m * 16) * ldc + col0;
; #pragma unroll
;                 for (int bj = 0; bj < 2; ++bj) { const f32x4 v0 = acc[ai][bj][m][0], v1 = acc[ai][bj][m][1];
;                     u32x4 w; w.x = cvt_pk_bf16(v0[0], v0[1]); w.y = cvt_pk_bf16(v0[2], v0[3]); w.z = cvt_pk_bf16(v1[0], v1[1]); w.w = cvt_pk_bf16(v1[2], v1[3]);
;                     *(u32x4*)(rowp + bj * HALF) = w; } }
; template <class Epi, class Sched>
; __device__ __forceinline__ void gemm_phase(LAS unsigned char* lds, const Gemm g, const Sched& S, const Epi& E, int tid) {
;     ...
;         if (!has_next) break;
; #pragma unroll
;         for (int a = 0; a < 2; ++a)
; #pragma unroll
;             for (int b = 0; b < 2; ++b)
; #pragma unroll
;                 for (int m = 0; m < 4; ++m)
; #pragma unroll
;                     for (int n = 0; n < 2; ++n) acc[a][b][m][n] = (f32x4){0.f, 0.f, 0.f, 0.f};
;         cur = nxt; cA = nA; cB = nB; ++ui;
;     }
;     PG8_WAIT_V(0);
;     if (wr == 0) PG8_BAR;
;     PG8_BAR;
.Lpeel_exit_plain:
	v_lshl_add_u32 v148, s60, 8, v140
	v_lshl_or_b32 v144, s61, 8, v142
	v_ashrrev_i32_e32 v145, 31, v144
	v_mad_i64_i32 v[146:147], s[0:1], v148, s74, 0
	v_cvt_pk_bf16_f32 v108, v108, v109
	v_cvt_pk_bf16_f32 v109, v110, v111
	v_cvt_pk_bf16_f32 v110, v104, v105
	v_or_b32_e32 v104, 16, v148
	v_lshl_add_u64 v[146:147], v[146:147], 1, s[14:15]
	v_lshlrev_b64 v[144:145], 1, v[144:145]
	v_mad_i64_i32 v[104:105], s[0:1], v104, s74, 0
	v_cvt_pk_bf16_f32 v92, v92, v93
	v_cvt_pk_bf16_f32 v93, v94, v95
	v_cvt_pk_bf16_f32 v94, v88, v89
	v_or_b32_e32 v88, 32, v148
	v_lshl_add_u64 v[146:147], v[146:147], 0, v[144:145]
	v_cvt_pk_bf16_f32 v111, v106, v107
	v_lshl_add_u64 v[104:105], v[104:105], 1, s[14:15]
	v_mad_i64_i32 v[88:89], s[0:1], v88, s74, 0
	v_cvt_pk_bf16_f32 v76, v76, v77
	v_cvt_pk_bf16_f32 v77, v78, v79
	v_cvt_pk_bf16_f32 v78, v72, v73
	v_or_b32_e32 v72, 48, v148
	v_cvt_pk_bf16_f32 v68, v68, v69
	v_cvt_pk_bf16_f32 v69, v70, v71
	v_cvt_pk_bf16_f32 v70, v64, v65
	v_add_u32_e32 v64, 0x80, v148
	v_cvt_pk_bf16_f32 v124, v124, v125
	v_cvt_pk_bf16_f32 v125, v126, v127
	v_cvt_pk_bf16_f32 v126, v120, v121
	v_cvt_pk_bf16_f32 v127, v122, v123
	global_store_dwordx4 v[146:147], v[108:111], off offset:256
	v_cvt_pk_bf16_f32 v95, v90, v91
	v_lshl_add_u64 v[88:89], v[88:89], 1, s[14:15]
	v_lshl_add_u64 v[108:109], v[104:105], 0, v[144:145]
	v_mad_i64_i32 v[72:73], s[0:1], v72, s74, 0
	v_mad_i64_i32 v[64:65], s[0:1], v64, s74, 0
	v_cvt_pk_bf16_f32 v44, v44, v45
	v_cvt_pk_bf16_f32 v45, v46, v47
	v_cvt_pk_bf16_f32 v46, v40, v41
	v_add_u32_e32 v40, 0x90, v148
	global_store_dwordx4 v[146:147], v[124:127], off
	v_cvt_pk_bf16_f32 v104, v116, v117
	v_cvt_pk_bf16_f32 v105, v118, v119
	v_cvt_pk_bf16_f32 v106, v112, v113
	v_cvt_pk_bf16_f32 v107, v114, v115
	global_store_dwordx4 v[108:109], v[92:95], off offset:256
	v_cvt_pk_bf16_f32 v79, v74, v75
	v_lshl_add_u64 v[72:73], v[72:73], 1, s[14:15]
	v_lshl_add_u64 v[92:93], v[88:89], 0, v[144:145]
	v_lshl_add_u64 v[64:65], v[64:65], 1, s[14:15]
	v_mad_i64_i32 v[40:41], s[0:1], v40, s74, 0
	v_cvt_pk_bf16_f32 v28, v28, v29
	v_cvt_pk_bf16_f32 v29, v30, v31
	v_cvt_pk_bf16_f32 v30, v24, v25
	v_add_u32_e32 v24, 0xa0, v148
	global_store_dwordx4 v[108:109], v[104:107], off
	v_cvt_pk_bf16_f32 v88, v100, v101
	v_cvt_pk_bf16_f32 v89, v102, v103
	v_cvt_pk_bf16_f32 v90, v96, v97
	v_cvt_pk_bf16_f32 v91, v98, v99
	global_store_dwordx4 v[92:93], v[76:79], off offset:256
	v_cvt_pk_bf16_f32 v74, v80, v81
	v_cvt_pk_bf16_f32 v75, v82, v83
	v_lshl_add_u64 v[76:77], v[72:73], 0, v[144:145]
	v_cvt_pk_bf16_f32 v72, v84, v85
	v_cvt_pk_bf16_f32 v73, v86, v87
	v_cvt_pk_bf16_f32 v71, v66, v67
	v_lshl_add_u64 v[64:65], v[64:65], 0, v[144:145]
	v_cvt_pk_bf16_f32 v47, v42, v43
	v_lshl_add_u64 v[40:41], v[40:41], 1, s[14:15]
	v_mad_i64_i32 v[24:25], s[0:1], v24, s74, 0
	v_cvt_pk_bf16_f32 v12, v12, v13
	v_cvt_pk_bf16_f32 v13, v14, v15
	v_cvt_pk_bf16_f32 v14, v8, v9
	v_add_u32_e32 v8, 0xb0, v148
	global_store_dwordx4 v[92:93], v[88:91], off
	global_store_dwordx4 v[76:77], v[72:75], off
	global_store_dwordx4 v[76:77], v[68:71], off offset:256
	v_cvt_pk_bf16_f32 v60, v60, v61
	v_cvt_pk_bf16_f32 v61, v62, v63
	v_cvt_pk_bf16_f32 v62, v56, v57
	v_cvt_pk_bf16_f32 v63, v58, v59
	global_store_dwordx4 v[64:65], v[44:47], off offset:256
	v_cvt_pk_bf16_f32 v31, v26, v27
	v_lshl_add_u64 v[24:25], v[24:25], 1, s[14:15]
	v_lshl_add_u64 v[44:45], v[40:41], 0, v[144:145]
	v_mad_i64_i32 v[8:9], s[0:1], v8, s74, 0
	global_store_dwordx4 v[64:65], v[60:63], off
	v_cvt_pk_bf16_f32 v40, v52, v53
	v_cvt_pk_bf16_f32 v41, v54, v55
	v_cvt_pk_bf16_f32 v42, v48, v49
	v_cvt_pk_bf16_f32 v43, v50, v51
	global_store_dwordx4 v[44:45], v[28:31], off offset:256
	v_cvt_pk_bf16_f32 v15, v10, v11
	v_lshl_add_u64 v[8:9], v[8:9], 1, s[14:15]
	v_lshl_add_u64 v[28:29], v[24:25], 0, v[144:145]
	global_store_dwordx4 v[44:45], v[40:43], off
	v_cvt_pk_bf16_f32 v24, v36, v37
	v_cvt_pk_bf16_f32 v25, v38, v39
	v_cvt_pk_bf16_f32 v26, v32, v33
	v_cvt_pk_bf16_f32 v27, v34, v35
	global_store_dwordx4 v[28:29], v[12:15], off offset:256
	v_cvt_pk_bf16_f32 v10, v16, v17
	v_cvt_pk_bf16_f32 v11, v18, v19
	v_lshl_add_u64 v[12:13], v[8:9], 0, v[144:145]
	v_cvt_pk_bf16_f32 v8, v20, v21
	v_cvt_pk_bf16_f32 v9, v22, v23
	v_cvt_pk_bf16_f32 v4, v4, v5
	v_cvt_pk_bf16_f32 v5, v6, v7
	v_cvt_pk_bf16_f32 v6, v0, v1
	v_cvt_pk_bf16_f32 v7, v2, v3
	s_and_b64 vcc, exec, s[36:37]
	s_mov_b32 s61, s63
	s_mov_b32 s60, s58
	s_mov_b64 s[34:35], s[40:41]
	s_mov_b64 s[44:45], s[38:39]
	global_store_dwordx4 v[28:29], v[24:27], off
	global_store_dwordx4 v[12:13], v[8:11], off
	global_store_dwordx4 v[12:13], v[4:7], off offset:256
	s_cbranch_vccz .LBB0_89
	s_waitcnt vmcnt(0)
	s_cmpk_gt_u32 s76, 0xff
	s_cbranch_scc1 .LBB0_68
	s_barrier
	s_branch .LBB0_68

; #define PG8_STAGE(bufoff, gbase, voff) do { _Pragma("unroll") for (int _i = 0; _i < 2; ++_i) \
;         __builtin_amdgcn_global_load_lds((const unsigned*)((const char*)(gbase) + (voff)[_i]), (LAS unsigned*)(lds + (bufoff) + ldsw + _i * 8192), 16, 0, 0); } while (0)
; #define PG8_LDA(dst, b, h) do { _Pragma("unroll") for (int m = 0; m < 4; ++m) _Pragma("unroll") for (int k = 0; k < 2; ++k) dst[m][k] = *(const LAS bf16x8*)(lds + PG8_SA(b, h) + aoff + m * 2048 + k * 1024); } while (0)
; #define PG8_LDB(dst, b, h) do { _Pragma("unroll") for (int n = 0; n < 2; ++n) _Pragma("unroll") for (int k = 0; k < 2; ++k) dst[n][k] = *(const LAS bf16x8*)(lds + PG8_SB(b, h) + boff + n * 2048 + k * 1024); } while (0)
; #define PG8_MMA(ai, bj, At, Bt) do { __builtin_amdgcn_s_setprio(1); _Pragma("unroll") for (int m = 0; m < 4; ++m) _Pragma("unroll") for (int n = 0; n < 2; ++n) _Pragma("unroll") for (int k = 0; k < 2; ++k) \
;         acc[ai][bj][m][n] = __builtin_amdgcn_mfma_f32_16x16x32_bf16(Bt[n][k], At[m][k], acc[ai][bj][m][n], 0, 0, 0); __builtin_amdgcn_s_setprio(0); } while (0)
; #define PG8_WAIT_L(n) asm volatile("s_waitcnt lgkmcnt(" #n ")" ::: "memory")
; template <class Epi, class Sched>
; __device__ __forceinline__ void gemm_phase(LAS unsigned char* lds, const Gemm g, const Sched& S, const Epi& E, int tid) {
;     ...
;         const bool has_next = S.next(ui + 1, nxt);
;         const char* nA = has_next ? (const char*)g.A + (size_t)nxt.pm * tstep : cA; const char* nB = has_next ? (const char*)g.Bt + (size_t)nxt.pn * tstep : cB;
;         for (int t = 0; t < nt; t += 2) {
;             const bool last = (t == nt - 2);
;             const char* a1 = cA + (size_t)(t + 1) * kstep;
;             const char* a2 = last ? nA : cA + (size_t)(t + 2) * kstep; const char* b2 = last ? nB : cB + (size_t)(t + 2) * kstep;
;             const char* a3 = a2 + kstep; const char* b3 = b2 + kstep;
;             PG8_LDB(B0, 0, 0); PG8_SCHED; PG8_LDA(At, 0, 0); PG8_STAGE(PG8_SA(1, 1), a1 + hstep, voffA);
;             PG8_WAIT_L(8); PG8_BAR; PG8_WAIT_L(0); PG8_MMA(0, 0, At, B0); PG8_BAR; PG8_SCHED;
;             PG8_LDB(B1, 0, 1); PG8_STAGE(PG8_SB(0, 0), b2, voffB);
;             PG8_BAR; PG8_WAIT_L(0); PG8_MMA(0, 1, At, B1); PG8_BAR;
;             PG8_LDA(At, 0, 1); PG8_STAGE(PG8_SA(0, 0), a2, voffA);
;             PG8_BAR; PG8_WAIT_L(0); PG8_MMA(1, 0, At, B0); PG8_BAR; PG8_SCHED;
.LBB0_114:
	s_ashr_i32 s25, s24, 31
	s_lshl_b64 s[0:1], s[24:25], 19
	v_cmp_lt_i64_e32 vcc, s[28:29], v[158:159]
	s_add_u32 s28, s26, s0
	s_addc_u32 s29, s27, s1
	s_and_b64 s[0:1], vcc, exec
	s_cselect_b32 s25, s29, s41
	s_cselect_b32 s53, s28, s40
	s_ashr_i32 s15, s14, 31
	s_lshl_b64 s[0:1], s[14:15], 19
	s_add_u32 s30, s19, s0
	s_addc_u32 s31, s44, s1
	s_and_b64 s[0:1], vcc, exec
	s_cselect_b32 s15, s31, s43
	s_cselect_b32 s55, s30, s42
	s_add_u32 s40, s40, 0x40080
	s_addc_u32 s41, s41, 0
	s_add_u32 s58, s42, 0x100
	s_addc_u32 s60, s43, 0
	s_mov_b32 s61, -2
	s_waitcnt vmcnt(0)
	s_add_u32 s0, s40, 0xfffc0080
	s_addc_u32 s1, s41, -1
	s_add_i32 s17, 0, 0x10000
	v_add_u32_e32 v160, s17, v143
	ds_read_b128 v[138:141], v160
	ds_read_b128 v[146:149], v160 offset:1024
	ds_read_b128 v[150:153], v160 offset:2048
	ds_read_b128 v[160:163], v160 offset:3072
	s_cmp_eq_u32 s61, 12
	s_cselect_b32 s43, s25, s1
	s_cselect_b32 s42, s53, s0
	s_cselect_b32 s35, s15, s60
	s_cselect_b32 s34, s55, s58
	v_lshl_add_u64 v[208:209], s[40:41], 0, v[134:135]
	s_add_i32 m0, s39, 0xc000
	ds_read_b128 v[164:167], v145
	ds_read_b128 v[168:171], v145 offset:1024
	ds_read_b128 v[184:187], v145 offset:2048
	ds_read_b128 v[188:191], v145 offset:3072
	ds_read_b128 v[192:195], v145 offset:4096
	ds_read_b128 v[196:199], v145 offset:5120
	ds_read_b128 v[200:203], v145 offset:6144
	ds_read_b128 v[204:207], v145 offset:7168
	global_load_lds_dwordx4 v[208:209], off
	v_lshl_add_u64 v[208:209], s[40:41], 0, v[136:137]
	s_add_i32 m0, s39, 0xe000
	s_nop 0
	global_load_lds_dwordx4 v[208:209], off
	s_waitcnt lgkmcnt(8)
	s_barrier
	s_waitcnt lgkmcnt(0)
	s_setprio 1
	s_waitcnt lgkmcnt(0)
	v_mfma_f32_16x16x32_bf16 v[124:127], v[138:141], v[164:167], 0
	v_mfma_f32_16x16x32_bf16 v[120:123], v[150:153], v[164:167], 0
	v_mfma_f32_16x16x32_bf16 v[108:111], v[138:141], v[184:187], 0
	v_mfma_f32_16x16x32_bf16 v[104:107], v[150:153], v[184:187], 0
	v_mfma_f32_16x16x32_bf16 v[92:95], v[138:141], v[192:195], 0
	v_mfma_f32_16x16x32_bf16 v[88:91], v[150:153], v[192:195], 0
	v_mfma_f32_16x16x32_bf16 v[76:79], v[138:141], v[200:203], 0
	v_mfma_f32_16x16x32_bf16 v[72:75], v[150:153], v[200:203], 0
	v_mfma_f32_16x16x32_bf16 v[124:127], v[146:149], v[168:171], v[124:127]
	v_mfma_f32_16x16x32_bf16 v[120:123], v[160:163], v[168:171], v[120:123]
	v_mfma_f32_16x16x32_bf16 v[108:111], v[146:149], v[188:191], v[108:111]
	v_mfma_f32_16x16x32_bf16 v[104:107], v[160:163], v[188:191], v[104:107]
	v_mfma_f32_16x16x32_bf16 v[92:95], v[146:149], v[196:199], v[92:95]
	v_mfma_f32_16x16x32_bf16 v[88:91], v[160:163], v[196:199], v[88:91]
	v_mfma_f32_16x16x32_bf16 v[76:79], v[146:149], v[204:207], v[76:79]
	v_mfma_f32_16x16x32_bf16 v[72:75], v[160:163], v[204:207], v[72:75]
	s_setprio 0
	s_barrier
	s_add_i32 s63, 0, 0x14000
	s_add_i32 s0, s17, s45
	v_add_u32_e32 v183, s63, v143
	v_lshl_add_u64 v[224:225], s[34:35], 0, v[154:155]
	s_mov_b32 m0, s0
	ds_read_b128 v[208:211], v183
	ds_read_b128 v[212:215], v183 offset:1024
	ds_read_b128 v[216:219], v183 offset:2048
	ds_read_b128 v[220:223], v183 offset:3072
	global_load_lds_dwordx4 v[224:225], off
	v_lshl_add_u64 v[226:227], s[34:35], 0, v[128:129]
	s_add_i32 m0, s0, 0x2000
	s_nop 0
	global_load_lds_dwordx4 v[226:227], off
	s_barrier
	s_waitcnt lgkmcnt(0)
	s_setprio 1
	s_waitcnt lgkmcnt(0)
	v_mfma_f32_16x16x32_bf16 v[116:119], v[208:211], v[164:167], 0
	v_mfma_f32_16x16x32_bf16 v[112:115], v[216:219], v[164:167], 0
	v_mfma_f32_16x16x32_bf16 v[100:103], v[208:211], v[184:187], 0
	v_mfma_f32_16x16x32_bf16 v[96:99], v[216:219], v[184:187], 0
	v_mfma_f32_16x16x32_bf16 v[84:87], v[208:211], v[192:195], 0
	v_mfma_f32_16x16x32_bf16 v[80:83], v[216:219], v[192:195], 0
	v_mfma_f32_16x16x32_bf16 v[68:71], v[208:211], v[200:203], 0
	v_mfma_f32_16x16x32_bf16 v[64:67], v[216:219], v[200:203], 0
	v_mfma_f32_16x16x32_bf16 v[116:119], v[212:215], v[168:171], v[116:119]
	v_mfma_f32_16x16x32_bf16 v[112:115], v[220:223], v[168:171], v[112:115]
	v_mfma_f32_16x16x32_bf16 v[100:103], v[212:215], v[188:191], v[100:103]
	v_mfma_f32_16x16x32_bf16 v[96:99], v[220:223], v[188:191], v[96:99]
	v_mfma_f32_16x16x32_bf16 v[84:87], v[212:215], v[196:199], v[84:87]
	v_mfma_f32_16x16x32_bf16 v[80:83], v[220:223], v[196:199], v[80:83]
	v_mfma_f32_16x16x32_bf16 v[68:71], v[212:215], v[204:207], v[68:71]
	v_mfma_f32_16x16x32_bf16 v[64:67], v[220:223], v[204:207], v[64:67]
	s_setprio 0
	s_mov_b32 m0, s39
	v_lshl_add_u64 v[228:229], s[42:43], 0, v[132:133]
	s_barrier
	ds_read_b128 v[164:167], v145 offset:16384
	ds_read_b128 v[168:171], v145 offset:17408
	ds_read_b128 v[184:187], v145 offset:18432
	ds_read_b128 v[188:191], v145 offset:19456
	ds_read_b128 v[192:195], v145 offset:20480
	ds_read_b128 v[196:199], v145 offset:21504
	ds_read_b128 v[200:203], v145 offset:22528
	ds_read_b128 v[204:207], v145 offset:23552
	global_load_lds_dwordx4 v[228:229], off
	v_lshl_add_u64 v[230:231], s[42:43], 0, v[130:131]
	s_mov_b32 m0, s47
	s_nop 0
	global_load_lds_dwordx4 v[230:231], off
	s_barrier
	s_waitcnt lgkmcnt(0)
	s_setprio 1
	s_waitcnt lgkmcnt(0)
	v_mfma_f32_16x16x32_bf16 v[60:63], v[138:141], v[164:167], 0
	v_mfma_f32_16x16x32_bf16 v[56:59], v[150:153], v[164:167], 0
	v_mfma_f32_16x16x32_bf16 v[44:47], v[138:141], v[184:187], 0
	v_mfma_f32_16x16x32_bf16 v[40:43], v[150:153], v[184:187], 0
	v_mfma_f32_16x16x32_bf16 v[28:31], v[138:141], v[192:195], 0
	v_mfma_f32_16x16x32_bf16 v[24:27], v[150:153], v[192:195], 0
	v_mfma_f32_16x16x32_bf16 v[12:15], v[138:141], v[200:203], 0
	v_mfma_f32_16x16x32_bf16 v[8:11], v[150:153], v[200:203], 0
	v_mfma_f32_16x16x32_bf16 v[60:63], v[146:149], v[168:171], v[60:63]
	v_mfma_f32_16x16x32_bf16 v[56:59], v[160:163], v[168:171], v[56:59]
	v_mfma_f32_16x16x32_bf16 v[44:47], v[146:149], v[188:191], v[44:47]
	v_mfma_f32_16x16x32_bf16 v[40:43], v[160:163], v[188:191], v[40:43]
	v_mfma_f32_16x16x32_bf16 v[28:31], v[146:149], v[196:199], v[28:31]
	v_mfma_f32_16x16x32_bf16 v[24:27], v[160:163], v[196:199], v[24:27]
	v_mfma_f32_16x16x32_bf16 v[12:15], v[146:149], v[204:207], v[12:15]
	v_mfma_f32_16x16x32_bf16 v[8:11], v[160:163], v[204:207], v[8:11]
	s_setprio 0
	s_barrier
; #define PG8_STAGE(bufoff, gbase, voff) do { _Pragma("unroll") for (int _i = 0; _i < 2; ++_i) \
;         __builtin_amdgcn_global_load_lds((const unsigned*)((const char*)(gbase) + (voff)[_i]), (LAS unsigned*)(lds + (bufoff) + ldsw + _i * 8192), 16, 0, 0); } while (0)
; #define PG8_LDA(dst, b, h) do { _Pragma("unroll") for (int m = 0; m < 4; ++m) _Pragma("unroll") for (int k = 0; k < 2; ++k) dst[m][k] = *(const LAS bf16x8*)(lds + PG8_SA(b, h) + aoff + m * 2048 + k * 1024); } while (0)
; #define PG8_LDB(dst, b, h) do { _Pragma("unroll") for (int n = 0; n < 2; ++n) _Pragma("unroll") for (int k = 0; k < 2; ++k) dst[n][k] = *(const LAS bf16x8*)(lds + PG8_SB(b, h) + boff + n * 2048 + k * 1024); } while (0)
; #define PG8_MMA(ai, bj, At, Bt) do { __builtin_amdgcn_s_setprio(1); _Pragma("unroll") for (int m = 0; m < 4; ++m) _Pragma("unroll") for (int n = 0; n < 2; ++n) _Pragma("unroll") for (int k = 0; k < 2; ++k) \
;         acc[ai][bj][m][n] = __builtin_amdgcn_mfma_f32_16x16x32_bf16(Bt[n][k], At[m][k], acc[ai][bj][m][n], 0, 0, 0); __builtin_amdgcn_s_setprio(0); } while (0)
; #define PG8_WAIT_V(n) asm volatile("s_waitcnt vmcnt(" #n ")" ::: "memory")
; #define PG8_WAIT_L(n) asm volatile("s_waitcnt lgkmcnt(" #n ")" ::: "memory")
; #define PG8_BAR __builtin_amdgcn_s_barrier()
; #define PG8_SCHED __builtin_amdgcn_sched_barrier(0)
; template <class Epi, class Sched>
; __device__ __forceinline__ void gemm_phase(LAS unsigned char* lds, const Gemm g, const Sched& S, const Epi& E, int tid) {
;     ...
;             PG8_STAGE(PG8_SB(0, 1), b2 + hstep, voffB);
;             PG8_WAIT_V(6); PG8_BAR; PG8_MMA(1, 1, At, B1); PG8_BAR;
;             PG8_LDB(B0, 1, 0); PG8_SCHED; PG8_LDA(At, 1, 0); PG8_STAGE(PG8_SA(0, 1), a2 + hstep, voffA);
;             PG8_WAIT_L(8); PG8_BAR; PG8_WAIT_L(0); PG8_MMA(0, 0, At, B0); PG8_BAR; PG8_SCHED;
;             PG8_LDB(B1, 1, 1); PG8_STAGE(PG8_SB(1, 0), b3, voffB);
;             PG8_BAR; PG8_WAIT_L(0); PG8_MMA(0, 1, At, B1); PG8_BAR;
	s_add_u32 s0, s34, 0x40000
	s_addc_u32 s1, s35, 0
	s_add_i32 s17, s63, s45
	v_lshl_add_u64 v[138:139], s[0:1], 0, v[154:155]
	s_mov_b32 m0, s17
	s_nop 0
	global_load_lds_dwordx4 v[138:139], off
	v_lshl_add_u64 v[138:139], s[0:1], 0, v[128:129]
	s_add_i32 m0, s17, 0x2000
	s_nop 0
	global_load_lds_dwordx4 v[138:139], off
	s_waitcnt vmcnt(6)
	s_barrier
	s_setprio 1
	v_mfma_f32_16x16x32_bf16 v[52:55], v[208:211], v[164:167], 0
	v_mfma_f32_16x16x32_bf16 v[48:51], v[216:219], v[164:167], 0
	v_mfma_f32_16x16x32_bf16 v[36:39], v[208:211], v[184:187], 0
	v_mfma_f32_16x16x32_bf16 v[32:35], v[216:219], v[184:187], 0
	v_mfma_f32_16x16x32_bf16 v[20:23], v[208:211], v[192:195], 0
	v_mfma_f32_16x16x32_bf16 v[16:19], v[216:219], v[192:195], 0
	v_mfma_f32_16x16x32_bf16 v[4:7], v[208:211], v[200:203], 0
	v_mfma_f32_16x16x32_bf16 v[0:3], v[216:219], v[200:203], 0
	v_mfma_f32_16x16x32_bf16 v[52:55], v[212:215], v[168:171], v[52:55]
	v_mfma_f32_16x16x32_bf16 v[48:51], v[220:223], v[168:171], v[48:51]
	v_mfma_f32_16x16x32_bf16 v[36:39], v[212:215], v[188:191], v[36:39]
	v_mfma_f32_16x16x32_bf16 v[32:35], v[220:223], v[188:191], v[32:35]
	v_mfma_f32_16x16x32_bf16 v[20:23], v[212:215], v[196:199], v[20:23]
	v_mfma_f32_16x16x32_bf16 v[16:19], v[220:223], v[196:199], v[16:19]
	v_mfma_f32_16x16x32_bf16 v[4:7], v[212:215], v[204:207], v[4:7]
	v_mfma_f32_16x16x32_bf16 v[0:3], v[220:223], v[204:207], v[0:3]
	s_setprio 0
	s_add_i32 s17, 0, 0x18000
	v_add_u32_e32 v160, s17, v143
	s_barrier
	ds_read_b128 v[138:141], v160
	ds_read_b128 v[146:149], v160 offset:1024
	ds_read_b128 v[150:153], v160 offset:2048
	ds_read_b128 v[160:163], v160 offset:3072
	s_add_u32 s0, s42, 0x40000
	s_addc_u32 s1, s43, 0
	s_mov_b32 m0, s48
	v_lshl_add_u64 v[208:209], s[0:1], 0, v[132:133]
	ds_read_b128 v[164:167], v145 offset:32768
	ds_read_b128 v[168:171], v145 offset:33792
	ds_read_b128 v[184:187], v145 offset:34816
	ds_read_b128 v[188:191], v145 offset:35840
	ds_read_b128 v[192:195], v145 offset:36864
	ds_read_b128 v[196:199], v145 offset:37888
	ds_read_b128 v[200:203], v145 offset:38912
	ds_read_b128 v[204:207], v145 offset:39936
	global_load_lds_dwordx4 v[208:209], off
	v_lshl_add_u64 v[208:209], s[0:1], 0, v[130:131]
	s_mov_b32 m0, s49
	s_nop 0
	global_load_lds_dwordx4 v[208:209], off
	s_waitcnt lgkmcnt(8)
	s_barrier
	s_waitcnt lgkmcnt(0)
	s_setprio 1
	s_waitcnt lgkmcnt(0)
	v_mfma_f32_16x16x32_bf16 v[124:127], v[138:141], v[164:167], v[124:127]
	v_mfma_f32_16x16x32_bf16 v[120:123], v[150:153], v[164:167], v[120:123]
	v_mfma_f32_16x16x32_bf16 v[108:111], v[138:141], v[184:187], v[108:111]
	v_mfma_f32_16x16x32_bf16 v[104:107], v[150:153], v[184:187], v[104:107]
	v_mfma_f32_16x16x32_bf16 v[92:95], v[138:141], v[192:195], v[92:95]
	v_mfma_f32_16x16x32_bf16 v[88:91], v[150:153], v[192:195], v[88:91]
	v_mfma_f32_16x16x32_bf16 v[76:79], v[138:141], v[200:203], v[76:79]
	v_mfma_f32_16x16x32_bf16 v[72:75], v[150:153], v[200:203], v[72:75]
	v_mfma_f32_16x16x32_bf16 v[124:127], v[146:149], v[168:171], v[124:127]
	v_mfma_f32_16x16x32_bf16 v[120:123], v[160:163], v[168:171], v[120:123]
	v_mfma_f32_16x16x32_bf16 v[108:111], v[146:149], v[188:191], v[108:111]
	v_mfma_f32_16x16x32_bf16 v[104:107], v[160:163], v[188:191], v[104:107]
	v_mfma_f32_16x16x32_bf16 v[92:95], v[146:149], v[196:199], v[92:95]
	v_mfma_f32_16x16x32_bf16 v[88:91], v[160:163], v[196:199], v[88:91]
	v_mfma_f32_16x16x32_bf16 v[76:79], v[146:149], v[204:207], v[76:79]
	v_mfma_f32_16x16x32_bf16 v[72:75], v[160:163], v[204:207], v[72:75]
	s_setprio 0
	s_barrier
	s_add_i32 s42, 0, 0x1c000
	s_add_i32 s0, s17, s45
	v_add_u32_e32 v183, s42, v143
	v_lshl_add_u64 v[224:225], v[224:225], 0, s[8:9]
	s_mov_b32 m0, s0
	ds_read_b128 v[208:211], v183
	ds_read_b128 v[212:215], v183 offset:1024
	ds_read_b128 v[216:219], v183 offset:2048
	ds_read_b128 v[220:223], v183 offset:3072
	global_load_lds_dwordx4 v[224:225], off
	v_lshl_add_u64 v[224:225], v[226:227], 0, s[8:9]
	s_add_i32 m0, s0, 0x2000
	s_nop 0
	global_load_lds_dwordx4 v[224:225], off
	s_barrier
; #define PG8_STAGE(bufoff, gbase, voff) do { _Pragma("unroll") for (int _i = 0; _i < 2; ++_i) \
;         __builtin_amdgcn_global_load_lds((const unsigned*)((const char*)(gbase) + (voff)[_i]), (LAS unsigned*)(lds + (bufoff) + ldsw + _i * 8192), 16, 0, 0); } while (0)
; #define PG8_LDA(dst, b, h) do { _Pragma("unroll") for (int m = 0; m < 4; ++m) _Pragma("unroll") for (int k = 0; k < 2; ++k) dst[m][k] = *(const LAS bf16x8*)(lds + PG8_SA(b, h) + aoff + m * 2048 + k * 1024); } while (0)
; #define PG8_MMA(ai, bj, At, Bt) do { __builtin_amdgcn_s_setprio(1); _Pragma("unroll") for (int m = 0; m < 4; ++m) _Pragma("unroll") for (int n = 0; n < 2; ++n) _Pragma("unroll") for (int k = 0; k < 2; ++k) \
;         acc[ai][bj][m][n] = __builtin_amdgcn_mfma_f32_16x16x32_bf16(Bt[n][k], At[m][k], acc[ai][bj][m][n], 0, 0, 0); __builtin_amdgcn_s_setprio(0); } while (0)
; #define PG8_WAIT_V(n) asm volatile("s_waitcnt vmcnt(" #n ")" ::: "memory")
; #define PG8_WAIT_L(n) asm volatile("s_waitcnt lgkmcnt(" #n ")" ::: "memory")
; #define PG8_BAR __builtin_amdgcn_s_barrier()
; #define PG8_SCHED __builtin_amdgcn_sched_barrier(0)
; template <class Epi, class Sched>
; __device__ __forceinline__ void gemm_phase(LAS unsigned char* lds, const Gemm g, const Sched& S, const Epi& E, int tid) {
;     ...
;             PG8_BAR; PG8_WAIT_L(0); PG8_MMA(0, 1, At, B1); PG8_BAR;
;             PG8_LDA(At, 1, 1); PG8_STAGE(PG8_SA(1, 0), a3, voffA);
;             PG8_BAR; PG8_WAIT_L(0); PG8_MMA(1, 0, At, B0); PG8_BAR; PG8_SCHED;
;             PG8_STAGE(PG8_SB(1, 1), b3 + hstep, voffB);
;             PG8_WAIT_V(6); PG8_BAR; PG8_MMA(1, 1, At, B1); PG8_BAR;
	s_waitcnt lgkmcnt(0)
	s_setprio 1
	s_waitcnt lgkmcnt(0)
	v_mfma_f32_16x16x32_bf16 v[116:119], v[208:211], v[164:167], v[116:119]
	v_mfma_f32_16x16x32_bf16 v[112:115], v[216:219], v[164:167], v[112:115]
	v_mfma_f32_16x16x32_bf16 v[100:103], v[208:211], v[184:187], v[100:103]
	v_mfma_f32_16x16x32_bf16 v[96:99], v[216:219], v[184:187], v[96:99]
	v_mfma_f32_16x16x32_bf16 v[84:87], v[208:211], v[192:195], v[84:87]
	v_mfma_f32_16x16x32_bf16 v[80:83], v[216:219], v[192:195], v[80:83]
	v_mfma_f32_16x16x32_bf16 v[68:71], v[208:211], v[200:203], v[68:71]
	v_mfma_f32_16x16x32_bf16 v[64:67], v[216:219], v[200:203], v[64:67]
	v_mfma_f32_16x16x32_bf16 v[116:119], v[212:215], v[168:171], v[116:119]
	v_mfma_f32_16x16x32_bf16 v[112:115], v[220:223], v[168:171], v[112:115]
	v_mfma_f32_16x16x32_bf16 v[100:103], v[212:215], v[188:191], v[100:103]
	v_mfma_f32_16x16x32_bf16 v[96:99], v[220:223], v[188:191], v[96:99]
	v_mfma_f32_16x16x32_bf16 v[84:87], v[212:215], v[196:199], v[84:87]
	v_mfma_f32_16x16x32_bf16 v[80:83], v[220:223], v[196:199], v[80:83]
	v_mfma_f32_16x16x32_bf16 v[68:71], v[212:215], v[204:207], v[68:71]
	v_mfma_f32_16x16x32_bf16 v[64:67], v[220:223], v[204:207], v[64:67]
	s_setprio 0
	s_mov_b32 m0, s6
	v_lshl_add_u64 v[224:225], v[228:229], 0, s[8:9]
	s_barrier
	ds_read_b128 v[164:167], v145 offset:49152
	ds_read_b128 v[168:171], v145 offset:50176
	ds_read_b128 v[184:187], v145 offset:51200
	ds_read_b128 v[188:191], v145 offset:52224
	ds_read_b128 v[192:195], v145 offset:53248
	ds_read_b128 v[196:199], v145 offset:54272
	ds_read_b128 v[200:203], v145 offset:55296
	ds_read_b128 v[204:207], v145 offset:56320
	global_load_lds_dwordx4 v[224:225], off
	v_lshl_add_u64 v[224:225], v[230:231], 0, s[8:9]
	s_mov_b32 m0, s50
	s_nop 0
	global_load_lds_dwordx4 v[224:225], off
	s_barrier
	s_waitcnt lgkmcnt(0)
	s_setprio 1
	s_waitcnt lgkmcnt(0)
	v_mfma_f32_16x16x32_bf16 v[60:63], v[138:141], v[164:167], v[60:63]
	v_mfma_f32_16x16x32_bf16 v[56:59], v[150:153], v[164:167], v[56:59]
	v_mfma_f32_16x16x32_bf16 v[44:47], v[138:141], v[184:187], v[44:47]
	v_mfma_f32_16x16x32_bf16 v[40:43], v[150:153], v[184:187], v[40:43]
	v_mfma_f32_16x16x32_bf16 v[28:31], v[138:141], v[192:195], v[28:31]
	v_mfma_f32_16x16x32_bf16 v[24:27], v[150:153], v[192:195], v[24:27]
	v_mfma_f32_16x16x32_bf16 v[12:15], v[138:141], v[200:203], v[12:15]
	v_mfma_f32_16x16x32_bf16 v[8:11], v[150:153], v[200:203], v[8:11]
	v_mfma_f32_16x16x32_bf16 v[60:63], v[146:149], v[168:171], v[60:63]
	v_mfma_f32_16x16x32_bf16 v[56:59], v[160:163], v[168:171], v[56:59]
	v_mfma_f32_16x16x32_bf16 v[44:47], v[146:149], v[188:191], v[44:47]
	v_mfma_f32_16x16x32_bf16 v[40:43], v[160:163], v[188:191], v[40:43]
	v_mfma_f32_16x16x32_bf16 v[28:31], v[146:149], v[196:199], v[28:31]
	v_mfma_f32_16x16x32_bf16 v[24:27], v[160:163], v[196:199], v[24:27]
	v_mfma_f32_16x16x32_bf16 v[12:15], v[146:149], v[204:207], v[12:15]
	v_mfma_f32_16x16x32_bf16 v[8:11], v[160:163], v[204:207], v[8:11]
	s_setprio 0
	s_barrier
	s_add_u32 s0, s34, 0x40080
	s_addc_u32 s1, s35, 0
	s_add_i32 s17, s42, s45
	v_lshl_add_u64 v[138:139], s[0:1], 0, v[154:155]
	s_mov_b32 m0, s17
	s_nop 0
	global_load_lds_dwordx4 v[138:139], off
	v_lshl_add_u64 v[138:139], s[0:1], 0, v[128:129]
	s_add_i32 m0, s17, 0x2000
	s_nop 0
	global_load_lds_dwordx4 v[138:139], off
	s_waitcnt vmcnt(6)
	s_barrier
	s_setprio 1
	v_mfma_f32_16x16x32_bf16 v[52:55], v[208:211], v[164:167], v[52:55]
	v_mfma_f32_16x16x32_bf16 v[48:51], v[216:219], v[164:167], v[48:51]
	v_mfma_f32_16x16x32_bf16 v[36:39], v[208:211], v[184:187], v[36:39]
	v_mfma_f32_16x16x32_bf16 v[32:35], v[216:219], v[184:187], v[32:35]
	v_mfma_f32_16x16x32_bf16 v[20:23], v[208:211], v[192:195], v[20:23]
	v_mfma_f32_16x16x32_bf16 v[16:19], v[216:219], v[192:195], v[16:19]
	v_mfma_f32_16x16x32_bf16 v[4:7], v[208:211], v[200:203], v[4:7]
	v_mfma_f32_16x16x32_bf16 v[0:3], v[216:219], v[200:203], v[0:3]
	v_mfma_f32_16x16x32_bf16 v[52:55], v[212:215], v[168:171], v[52:55]
	v_mfma_f32_16x16x32_bf16 v[48:51], v[220:223], v[168:171], v[48:51]
	v_mfma_f32_16x16x32_bf16 v[36:39], v[212:215], v[188:191], v[36:39]
	v_mfma_f32_16x16x32_bf16 v[32:35], v[220:223], v[188:191], v[32:35]
	v_mfma_f32_16x16x32_bf16 v[20:23], v[212:215], v[196:199], v[20:23]
	v_mfma_f32_16x16x32_bf16 v[16:19], v[220:223], v[196:199], v[16:19]
	v_mfma_f32_16x16x32_bf16 v[4:7], v[212:215], v[204:207], v[4:7]
	v_mfma_f32_16x16x32_bf16 v[0:3], v[220:223], v[204:207], v[0:3]
	s_setprio 0
	s_add_i32 s61, s61, 2
	s_add_u32 s40, s40, 0x100
	s_addc_u32 s41, s41, 0
	s_add_u32 s58, s58, 0x100
	s_addc_u32 s60, s60, 0
	s_cmp_gt_u32 s61, 13
	s_barrier
	s_cbranch_scc1 .Lpeel_exit_swiglu

; __device__ __forceinline__ unsigned cvt_pk_bf16_nv(float lo, float hi) { return cvt_pk_bf16(lo, hi); }
;     __device__ __forceinline__ void operator()(const f32x4 (&acc)[2][2][4][2], const Unit& u, int wr, int wc, int fr, int fq) const {
;         const int row0 = u.pm * BM + wr * 64 + fr, col0 = u.pn * HALF + wc * 32 + 8 * fq;
; #pragma unroll
;         for (int ai = 0; ai < 2; ++ai)
; #pragma unroll
;             for (int m = 0; m < 4; ++m) { bf16_t* rowp = O + (size_t)(row0 + ai * HALF + m * 16) * ldc + col0;
;                 float h[8], ex[8];
; #pragma unroll
;                 for (int q = 0; q < 8; ++q) ex[q] = __builtin_amdgcn_exp2f(acc[ai][0][m][q >> 2][q & 3] * -1.4426950408889634f);
; #pragma unroll
;                 for (int q = 0; q < 8; ++q) ex[q] = __builtin_amdgcn_rcpf(1.0f + ex[q]);
; #pragma unroll
;                 for (int q = 0; q < 8; ++q) h[q] = (acc[ai][0][m][q >> 2][q & 3] * acc[ai][1][m][q >> 2][q & 3]) * ex[q];
;                 u32x4 w; w.x = cvt_pk_bf16_nv(h[0], h[1]); w.y = cvt_pk_bf16_nv(h[2], h[3]); w.z = cvt_pk_bf16_nv(h[4], h[5]); w.w = cvt_pk_bf16_nv(h[6], h[7]);
;                 *(u32x4*)rowp = w; }
.Lpeel_exit_swiglu:
	v_mul_f32_e32 v148, 0xbfb8aa3b, v124
	v_mul_f32_e32 v149, 0xbfb8aa3b, v125
	v_mul_f32_e32 v150, 0xbfb8aa3b, v126
	v_mul_f32_e32 v151, 0xbfb8aa3b, v127
	v_mul_f32_e32 v152, 0xbfb8aa3b, v120
	v_mul_f32_e32 v153, 0xbfb8aa3b, v121
	v_exp_f32_e32 v148, v148
	v_exp_f32_e32 v149, v149
	v_exp_f32_e32 v150, v150
	v_exp_f32_e32 v151, v151
	v_exp_f32_e32 v152, v152
	v_exp_f32_e32 v153, v153
	v_mul_f32_e32 v160, 0xbfb8aa3b, v122
	v_mul_f32_e32 v161, 0xbfb8aa3b, v123
	v_exp_f32_e32 v160, v160
	v_exp_f32_e32 v161, v161
	v_add_f32_e32 v148, 1.0, v148
	v_add_f32_e32 v149, 1.0, v149
	v_add_f32_e32 v150, 1.0, v150
	v_add_f32_e32 v151, 1.0, v151
	v_add_f32_e32 v152, 1.0, v152
	v_add_f32_e32 v153, 1.0, v153
	v_rcp_f32_e32 v148, v148
	v_rcp_f32_e32 v149, v149
	v_rcp_f32_e32 v150, v150
	v_rcp_f32_e32 v151, v151
	v_rcp_f32_e32 v152, v152
	v_rcp_f32_e32 v153, v153
	v_add_f32_e32 v160, 1.0, v160
	v_add_f32_e32 v161, 1.0, v161
	v_rcp_f32_e32 v160, v160
	v_rcp_f32_e32 v161, v161
	v_lshl_or_b32 v140, s52, 7, v144
	v_pk_mul_f32 v[118:119], v[126:127], v[118:119]
	v_pk_mul_f32 v[116:117], v[124:125], v[116:117]
	v_pk_mul_f32 v[112:113], v[120:121], v[112:113]
	v_lshl_add_u32 v162, s38, 8, v142
	v_ashrrev_i32_e32 v141, 31, v140
	v_mov_b64_e32 v[138:139], s[22:23]
	v_pk_mul_f32 v[116:117], v[148:149], v[116:117]
	v_pk_mul_f32 v[118:119], v[150:151], v[118:119]
	v_pk_mul_f32 v[114:115], v[122:123], v[114:115]
	v_pk_mul_f32 v[112:113], v[152:153], v[112:113]
	v_mad_i64_i32 v[146:147], s[0:1], v162, s99, v[138:139]
	v_lshlrev_b64 v[140:141], 1, v[140:141]
	v_cvt_pk_bf16_f32 v116, v116, v117
	v_cvt_pk_bf16_f32 v117, v118, v119
	v_cvt_pk_bf16_f32 v118, v112, v113
	v_pk_mul_f32 v[112:113], v[160:161], v[114:115]
	v_lshl_add_u64 v[146:147], v[146:147], 0, v[140:141]
	v_cvt_pk_bf16_f32 v119, v112, v113
	global_store_dwordx4 v[146:147], v[116:119], off
	v_mul_f32_e32 v114, 0xbfb8aa3b, v108
	v_mul_f32_e32 v115, 0xbfb8aa3b, v109
	v_mul_f32_e32 v116, 0xbfb8aa3b, v110
	v_mul_f32_e32 v117, 0xbfb8aa3b, v111
	v_mul_f32_e32 v118, 0xbfb8aa3b, v104
	v_mul_f32_e32 v119, 0xbfb8aa3b, v105
	v_exp_f32_e32 v114, v114
	v_exp_f32_e32 v115, v115
	v_exp_f32_e32 v116, v116
	v_exp_f32_e32 v117, v117
	v_exp_f32_e32 v118, v118
	v_exp_f32_e32 v119, v119
	v_mul_f32_e32 v120, 0xbfb8aa3b, v106
	v_mul_f32_e32 v121, 0xbfb8aa3b, v107
	v_exp_f32_e32 v120, v120
	v_exp_f32_e32 v121, v121
	v_add_f32_e32 v114, 1.0, v114
	v_add_f32_e32 v115, 1.0, v115
	v_add_f32_e32 v116, 1.0, v116
	v_add_f32_e32 v117, 1.0, v117
	v_add_f32_e32 v118, 1.0, v118
	v_add_f32_e32 v119, 1.0, v119
	v_rcp_f32_e32 v114, v114
	v_rcp_f32_e32 v115, v115
	v_rcp_f32_e32 v116, v116
	v_rcp_f32_e32 v117, v117
	v_rcp_f32_e32 v118, v118
	v_rcp_f32_e32 v119, v119
	v_add_f32_e32 v120, 1.0, v120
	v_add_f32_e32 v121, 1.0, v121
	v_rcp_f32_e32 v120, v120
	v_rcp_f32_e32 v121, v121
	v_pk_mul_f32 v[102:103], v[110:111], v[102:103]
	v_pk_mul_f32 v[100:101], v[108:109], v[100:101]
	v_pk_mul_f32 v[96:97], v[104:105], v[96:97]
	v_or_b32_e32 v112, 16, v162
	v_pk_mul_f32 v[100:101], v[114:115], v[100:101]
	v_pk_mul_f32 v[102:103], v[116:117], v[102:103]
	v_pk_mul_f32 v[98:99], v[106:107], v[98:99]
	v_pk_mul_f32 v[96:97], v[118:119], v[96:97]
	v_mad_i64_i32 v[112:113], s[0:1], v112, s99, v[138:139]
	v_cvt_pk_bf16_f32 v100, v100, v101
	v_cvt_pk_bf16_f32 v101, v102, v103
	v_cvt_pk_bf16_f32 v102, v96, v97
	v_pk_mul_f32 v[96:97], v[120:121], v[98:99]
	v_lshl_add_u64 v[112:113], v[112:113], 0, v[140:141]
	v_cvt_pk_bf16_f32 v103, v96, v97
	global_store_dwordx4 v[112:113], v[100:103], off
	v_mul_f32_e32 v98, 0xbfb8aa3b, v92
	v_mul_f32_e32 v99, 0xbfb8aa3b, v93
	v_mul_f32_e32 v100, 0xbfb8aa3b, v94
	v_mul_f32_e32 v101, 0xbfb8aa3b, v95
	v_mul_f32_e32 v102, 0xbfb8aa3b, v88
	v_mul_f32_e32 v103, 0xbfb8aa3b, v89
	v_exp_f32_e32 v98, v98
	v_exp_f32_e32 v99, v99
	v_exp_f32_e32 v100, v100
	v_exp_f32_e32 v101, v101
	v_exp_f32_e32 v102, v102
	v_exp_f32_e32 v103, v103
	v_mul_f32_e32 v104, 0xbfb8aa3b, v90
	v_mul_f32_e32 v105, 0xbfb8aa3b, v91
	v_exp_f32_e32 v104, v104
	v_exp_f32_e32 v105, v105
	v_add_f32_e32 v98, 1.0, v98
	v_add_f32_e32 v99, 1.0, v99
	v_add_f32_e32 v100, 1.0, v100
	v_add_f32_e32 v101, 1.0, v101
	v_add_f32_e32 v102, 1.0, v102
	v_add_f32_e32 v103, 1.0, v103
	v_rcp_f32_e32 v98, v98
	v_rcp_f32_e32 v99, v99
	v_rcp_f32_e32 v100, v100
	v_rcp_f32_e32 v101, v101
	v_rcp_f32_e32 v102, v102
	v_rcp_f32_e32 v103, v103
	v_add_f32_e32 v104, 1.0, v104
	v_add_f32_e32 v105, 1.0, v105
	v_rcp_f32_e32 v104, v104
	v_rcp_f32_e32 v105, v105
	v_pk_mul_f32 v[86:87], v[94:95], v[86:87]
	v_pk_mul_f32 v[84:85], v[92:93], v[84:85]
	v_pk_mul_f32 v[80:81], v[88:89], v[80:81]
	v_or_b32_e32 v96, 32, v162
	v_pk_mul_f32 v[84:85], v[98:99], v[84:85]
	v_pk_mul_f32 v[86:87], v[100:101], v[86:87]
	v_pk_mul_f32 v[82:83], v[90:91], v[82:83]
	v_pk_mul_f32 v[80:81], v[102:103], v[80:81]
	v_mad_i64_i32 v[96:97], s[0:1], v96, s99, v[138:139]
	v_cvt_pk_bf16_f32 v84, v84, v85
	v_cvt_pk_bf16_f32 v85, v86, v87
	v_cvt_pk_bf16_f32 v86, v80, v81
	v_pk_mul_f32 v[80:81], v[104:105], v[82:83]
	v_lshl_add_u64 v[96:97], v[96:97], 0, v[140:141]
	v_cvt_pk_bf16_f32 v87, v80, v81
	global_store_dwordx4 v[96:97], v[84:87], off
	v_mul_f32_e32 v82, 0xbfb8aa3b, v76
	v_mul_f32_e32 v83, 0xbfb8aa3b, v77
	v_mul_f32_e32 v84, 0xbfb8aa3b, v78
	v_mul_f32_e32 v85, 0xbfb8aa3b, v79
	v_mul_f32_e32 v86, 0xbfb8aa3b, v72
	v_mul_f32_e32 v87, 0xbfb8aa3b, v73
	v_exp_f32_e32 v82, v82
	v_exp_f32_e32 v83, v83
	v_exp_f32_e32 v84, v84
	v_exp_f32_e32 v85, v85
	v_exp_f32_e32 v86, v86
	v_exp_f32_e32 v87, v87
	v_mul_f32_e32 v88, 0xbfb8aa3b, v74
	v_mul_f32_e32 v89, 0xbfb8aa3b, v75
	v_exp_f32_e32 v88, v88
	v_exp_f32_e32 v89, v89
	v_add_f32_e32 v82, 1.0, v82
; __device__ __forceinline__ unsigned cvt_pk_bf16_nv(float lo, float hi) { return cvt_pk_bf16(lo, hi); }
;     __device__ __forceinline__ void operator()(const f32x4 (&acc)[2][2][4][2], const Unit& u, int wr, int wc, int fr, int fq) const {
;     ...
;             for (int m = 0; m < 4; ++m) { bf16_t* rowp = O + (size_t)(row0 + ai * HALF + m * 16) * ldc + col0;
;                 float h[8], ex[8];
; #pragma unroll
;                 for (int q = 0; q < 8; ++q) ex[q] = __builtin_amdgcn_exp2f(acc[ai][0][m][q >> 2][q & 3] * -1.4426950408889634f);
; #pragma unroll
;                 for (int q = 0; q < 8; ++q) ex[q] = __builtin_amdgcn_rcpf(1.0f + ex[q]);
; #pragma unroll
;                 for (int q = 0; q < 8; ++q) h[q] = (acc[ai][0][m][q >> 2][q & 3] * acc[ai][1][m][q >> 2][q & 3]) * ex[q];
;                 u32x4 w; w.x = cvt_pk_bf16_nv(h[0], h[1]); w.y = cvt_pk_bf16_nv(h[2], h[3]); w.z = cvt_pk_bf16_nv(h[4], h[5]); w.w = cvt_pk_bf16_nv(h[6], h[7]);
;                 *(u32x4*)rowp = w; }
	v_add_f32_e32 v83, 1.0, v83
	v_add_f32_e32 v84, 1.0, v84
	v_add_f32_e32 v85, 1.0, v85
	v_add_f32_e32 v86, 1.0, v86
	v_add_f32_e32 v87, 1.0, v87
	v_rcp_f32_e32 v82, v82
	v_rcp_f32_e32 v83, v83
	v_rcp_f32_e32 v84, v84
	v_rcp_f32_e32 v85, v85
	v_rcp_f32_e32 v86, v86
	v_rcp_f32_e32 v87, v87
	v_add_f32_e32 v88, 1.0, v88
	v_add_f32_e32 v89, 1.0, v89
	v_rcp_f32_e32 v88, v88
	v_rcp_f32_e32 v89, v89
	v_pk_mul_f32 v[70:71], v[78:79], v[70:71]
	v_pk_mul_f32 v[68:69], v[76:77], v[68:69]
	v_pk_mul_f32 v[64:65], v[72:73], v[64:65]
	v_or_b32_e32 v80, 48, v162
	v_pk_mul_f32 v[68:69], v[82:83], v[68:69]
	v_pk_mul_f32 v[70:71], v[84:85], v[70:71]
	v_pk_mul_f32 v[66:67], v[74:75], v[66:67]
	v_pk_mul_f32 v[64:65], v[86:87], v[64:65]
	v_mad_i64_i32 v[80:81], s[0:1], v80, s99, v[138:139]
	v_cvt_pk_bf16_f32 v68, v68, v69
	v_cvt_pk_bf16_f32 v69, v70, v71
	v_cvt_pk_bf16_f32 v70, v64, v65
	v_pk_mul_f32 v[64:65], v[88:89], v[66:67]
	v_lshl_add_u64 v[80:81], v[80:81], 0, v[140:141]
	v_cvt_pk_bf16_f32 v71, v64, v65
	global_store_dwordx4 v[80:81], v[68:71], off
	v_mul_f32_e32 v66, 0xbfb8aa3b, v60
	v_mul_f32_e32 v67, 0xbfb8aa3b, v61
	v_mul_f32_e32 v68, 0xbfb8aa3b, v62
	v_mul_f32_e32 v69, 0xbfb8aa3b, v63
	v_mul_f32_e32 v70, 0xbfb8aa3b, v56
	v_mul_f32_e32 v71, 0xbfb8aa3b, v57
	v_exp_f32_e32 v66, v66
	v_exp_f32_e32 v67, v67
	v_exp_f32_e32 v68, v68
	v_exp_f32_e32 v69, v69
	v_exp_f32_e32 v70, v70
	v_exp_f32_e32 v71, v71
	v_mul_f32_e32 v72, 0xbfb8aa3b, v58
	v_mul_f32_e32 v73, 0xbfb8aa3b, v59
	v_exp_f32_e32 v72, v72
	v_exp_f32_e32 v73, v73
	v_add_f32_e32 v66, 1.0, v66
	v_add_f32_e32 v67, 1.0, v67
	v_add_f32_e32 v68, 1.0, v68
	v_add_f32_e32 v69, 1.0, v69
	v_add_f32_e32 v70, 1.0, v70
	v_add_f32_e32 v71, 1.0, v71
	v_rcp_f32_e32 v66, v66
	v_rcp_f32_e32 v67, v67
	v_rcp_f32_e32 v68, v68
	v_rcp_f32_e32 v69, v69
	v_rcp_f32_e32 v70, v70
	v_rcp_f32_e32 v71, v71
	v_add_f32_e32 v72, 1.0, v72
	v_add_f32_e32 v73, 1.0, v73
	v_rcp_f32_e32 v72, v72
	v_rcp_f32_e32 v73, v73
	v_pk_mul_f32 v[54:55], v[62:63], v[54:55]
	v_pk_mul_f32 v[52:53], v[60:61], v[52:53]
	v_pk_mul_f32 v[48:49], v[56:57], v[48:49]
	v_add_u32_e32 v64, 0x80, v162
	v_pk_mul_f32 v[52:53], v[66:67], v[52:53]
	v_pk_mul_f32 v[54:55], v[68:69], v[54:55]
	v_pk_mul_f32 v[50:51], v[58:59], v[50:51]
	v_pk_mul_f32 v[48:49], v[70:71], v[48:49]
	v_mad_i64_i32 v[64:65], s[0:1], v64, s99, v[138:139]
	v_cvt_pk_bf16_f32 v52, v52, v53
	v_cvt_pk_bf16_f32 v53, v54, v55
	v_cvt_pk_bf16_f32 v54, v48, v49
	v_pk_mul_f32 v[48:49], v[72:73], v[50:51]
	v_lshl_add_u64 v[64:65], v[64:65], 0, v[140:141]
	v_cvt_pk_bf16_f32 v55, v48, v49
	global_store_dwordx4 v[64:65], v[52:55], off
	v_mul_f32_e32 v50, 0xbfb8aa3b, v44
	v_mul_f32_e32 v51, 0xbfb8aa3b, v45
	v_mul_f32_e32 v52, 0xbfb8aa3b, v46
	v_mul_f32_e32 v53, 0xbfb8aa3b, v47
	v_mul_f32_e32 v54, 0xbfb8aa3b, v40
	v_mul_f32_e32 v55, 0xbfb8aa3b, v41
	v_exp_f32_e32 v50, v50
	v_exp_f32_e32 v51, v51
	v_exp_f32_e32 v52, v52
	v_exp_f32_e32 v53, v53
	v_exp_f32_e32 v54, v54
	v_exp_f32_e32 v55, v55
	v_mul_f32_e32 v56, 0xbfb8aa3b, v42
	v_mul_f32_e32 v57, 0xbfb8aa3b, v43
	v_exp_f32_e32 v56, v56
	v_exp_f32_e32 v57, v57
	v_add_f32_e32 v50, 1.0, v50
	v_add_f32_e32 v51, 1.0, v51
	v_add_f32_e32 v52, 1.0, v52
	v_add_f32_e32 v53, 1.0, v53
	v_add_f32_e32 v54, 1.0, v54
	v_add_f32_e32 v55, 1.0, v55
	v_rcp_f32_e32 v50, v50
	v_rcp_f32_e32 v51, v51
	v_rcp_f32_e32 v52, v52
	v_rcp_f32_e32 v53, v53
	v_rcp_f32_e32 v54, v54
	v_rcp_f32_e32 v55, v55
	v_add_f32_e32 v56, 1.0, v56
	v_add_f32_e32 v57, 1.0, v57
	v_rcp_f32_e32 v56, v56
	v_rcp_f32_e32 v57, v57
	v_pk_mul_f32 v[38:39], v[46:47], v[38:39]
	v_pk_mul_f32 v[36:37], v[44:45], v[36:37]
	v_pk_mul_f32 v[32:33], v[40:41], v[32:33]
	v_add_u32_e32 v48, 0x90, v162
	v_pk_mul_f32 v[36:37], v[50:51], v[36:37]
	v_pk_mul_f32 v[38:39], v[52:53], v[38:39]
; __device__ __forceinline__ unsigned cvt_pk_bf16_nv(float lo, float hi) { return cvt_pk_bf16(lo, hi); }
; #define PG8_WAIT_V(n) asm volatile("s_waitcnt vmcnt(" #n ")" ::: "memory")
; #define PG8_BAR __builtin_amdgcn_s_barrier()
;     __device__ __forceinline__ void operator()(const f32x4 (&acc)[2][2][4][2], const Unit& u, int wr, int wc, int fr, int fq) const {
;     ...
;             for (int m = 0; m < 4; ++m) { bf16_t* rowp = O + (size_t)(row0 + ai * HALF + m * 16) * ldc + col0;
;                 float h[8], ex[8];
; #pragma unroll
;                 for (int q = 0; q < 8; ++q) ex[q] = __builtin_amdgcn_exp2f(acc[ai][0][m][q >> 2][q & 3] * -1.4426950408889634f);
; #pragma unroll
;                 for (int q = 0; q < 8; ++q) ex[q] = __builtin_amdgcn_rcpf(1.0f + ex[q]);
; #pragma unroll
;                 for (int q = 0; q < 8; ++q) h[q] = (acc[ai][0][m][q >> 2][q & 3] * acc[ai][1][m][q >> 2][q & 3]) * ex[q];
;                 u32x4 w; w.x = cvt_pk_bf16_nv(h[0], h[1]); w.y = cvt_pk_bf16_nv(h[2], h[3]); w.z = cvt_pk_bf16_nv(h[4], h[5]); w.w = cvt_pk_bf16_nv(h[6], h[7]);
;                 *(u32x4*)rowp = w; }
; template <class Epi, class Sched>
; __device__ __forceinline__ void gemm_phase(LAS unsigned char* lds, const Gemm g, const Sched& S, const Epi& E, int tid) {
;     ...
;         if (!has_next) break;
; #pragma unroll
;         for (int a = 0; a < 2; ++a)
; #pragma unroll
;             for (int b = 0; b < 2; ++b)
; #pragma unroll
;                 for (int m = 0; m < 4; ++m)
; #pragma unroll
;                     for (int n = 0; n < 2; ++n) acc[a][b][m][n] = (f32x4){0.f, 0.f, 0.f, 0.f};
;         cur = nxt; cA = nA; cB = nB; ++ui;
;     }
;     PG8_WAIT_V(0);
;     if (wr == 0) PG8_BAR;
	v_pk_mul_f32 v[34:35], v[42:43], v[34:35]
	v_pk_mul_f32 v[32:33], v[54:55], v[32:33]
	v_mad_i64_i32 v[48:49], s[0:1], v48, s99, v[138:139]
	v_cvt_pk_bf16_f32 v36, v36, v37
	v_cvt_pk_bf16_f32 v37, v38, v39
	v_cvt_pk_bf16_f32 v38, v32, v33
	v_pk_mul_f32 v[32:33], v[56:57], v[34:35]
	v_lshl_add_u64 v[48:49], v[48:49], 0, v[140:141]
	v_cvt_pk_bf16_f32 v39, v32, v33
	global_store_dwordx4 v[48:49], v[36:39], off
	v_mul_f32_e32 v34, 0xbfb8aa3b, v28
	v_mul_f32_e32 v35, 0xbfb8aa3b, v29
	v_mul_f32_e32 v36, 0xbfb8aa3b, v30
	v_mul_f32_e32 v37, 0xbfb8aa3b, v31
	v_mul_f32_e32 v38, 0xbfb8aa3b, v24
	v_mul_f32_e32 v39, 0xbfb8aa3b, v25
	v_exp_f32_e32 v34, v34
	v_exp_f32_e32 v35, v35
	v_exp_f32_e32 v36, v36
	v_exp_f32_e32 v37, v37
	v_exp_f32_e32 v38, v38
	v_exp_f32_e32 v39, v39
	v_mul_f32_e32 v40, 0xbfb8aa3b, v26
	v_mul_f32_e32 v41, 0xbfb8aa3b, v27
	v_exp_f32_e32 v40, v40
	v_exp_f32_e32 v41, v41
	v_add_f32_e32 v34, 1.0, v34
	v_add_f32_e32 v35, 1.0, v35
	v_add_f32_e32 v36, 1.0, v36
	v_add_f32_e32 v37, 1.0, v37
	v_add_f32_e32 v38, 1.0, v38
	v_add_f32_e32 v39, 1.0, v39
	v_rcp_f32_e32 v34, v34
	v_rcp_f32_e32 v35, v35
	v_rcp_f32_e32 v36, v36
	v_rcp_f32_e32 v37, v37
	v_rcp_f32_e32 v38, v38
	v_rcp_f32_e32 v39, v39
	v_add_f32_e32 v40, 1.0, v40
	v_add_f32_e32 v41, 1.0, v41
	v_rcp_f32_e32 v40, v40
	v_rcp_f32_e32 v41, v41
	v_pk_mul_f32 v[22:23], v[30:31], v[22:23]
	v_pk_mul_f32 v[20:21], v[28:29], v[20:21]
	v_pk_mul_f32 v[16:17], v[24:25], v[16:17]
	v_add_u32_e32 v32, 0xa0, v162
	v_pk_mul_f32 v[20:21], v[34:35], v[20:21]
	v_pk_mul_f32 v[22:23], v[36:37], v[22:23]
	v_pk_mul_f32 v[18:19], v[26:27], v[18:19]
	v_pk_mul_f32 v[16:17], v[38:39], v[16:17]
	v_mad_i64_i32 v[32:33], s[0:1], v32, s99, v[138:139]
	v_cvt_pk_bf16_f32 v20, v20, v21
	v_cvt_pk_bf16_f32 v21, v22, v23
	v_cvt_pk_bf16_f32 v22, v16, v17
	v_pk_mul_f32 v[16:17], v[40:41], v[18:19]
	v_lshl_add_u64 v[32:33], v[32:33], 0, v[140:141]
	v_cvt_pk_bf16_f32 v23, v16, v17
	global_store_dwordx4 v[32:33], v[20:23], off
	v_mul_f32_e32 v18, 0xbfb8aa3b, v12
	v_mul_f32_e32 v19, 0xbfb8aa3b, v13
	v_mul_f32_e32 v20, 0xbfb8aa3b, v14
	v_mul_f32_e32 v21, 0xbfb8aa3b, v15
	v_mul_f32_e32 v22, 0xbfb8aa3b, v8
	v_mul_f32_e32 v23, 0xbfb8aa3b, v9
	v_exp_f32_e32 v18, v18
	v_exp_f32_e32 v19, v19
	v_exp_f32_e32 v20, v20
	v_exp_f32_e32 v21, v21
	v_exp_f32_e32 v22, v22
	v_exp_f32_e32 v23, v23
	v_mul_f32_e32 v24, 0xbfb8aa3b, v10
	v_mul_f32_e32 v25, 0xbfb8aa3b, v11
	v_exp_f32_e32 v24, v24
	v_exp_f32_e32 v25, v25
	v_add_f32_e32 v18, 1.0, v18
	v_add_f32_e32 v19, 1.0, v19
	v_add_f32_e32 v20, 1.0, v20
	v_add_f32_e32 v21, 1.0, v21
	v_add_f32_e32 v22, 1.0, v22
	v_add_f32_e32 v23, 1.0, v23
	v_rcp_f32_e32 v18, v18
	v_rcp_f32_e32 v19, v19
	v_rcp_f32_e32 v20, v20
	v_rcp_f32_e32 v21, v21
	v_rcp_f32_e32 v22, v22
	v_rcp_f32_e32 v23, v23
	v_add_f32_e32 v24, 1.0, v24
	v_add_f32_e32 v25, 1.0, v25
	v_rcp_f32_e32 v24, v24
	v_rcp_f32_e32 v25, v25
	v_pk_mul_f32 v[6:7], v[14:15], v[6:7]
	v_pk_mul_f32 v[4:5], v[12:13], v[4:5]
	v_pk_mul_f32 v[0:1], v[8:9], v[0:1]
	v_add_u32_e32 v16, 0xb0, v162
	v_pk_mul_f32 v[4:5], v[18:19], v[4:5]
	v_pk_mul_f32 v[6:7], v[20:21], v[6:7]
	v_pk_mul_f32 v[2:3], v[10:11], v[2:3]
	v_pk_mul_f32 v[0:1], v[22:23], v[0:1]
	v_mad_i64_i32 v[16:17], s[0:1], v16, s99, v[138:139]
	v_cvt_pk_bf16_f32 v4, v4, v5
	v_cvt_pk_bf16_f32 v5, v6, v7
	v_cvt_pk_bf16_f32 v6, v0, v1
	v_pk_mul_f32 v[0:1], v[24:25], v[2:3]
	v_lshl_add_u64 v[16:17], v[16:17], 0, v[140:141]
	v_cvt_pk_bf16_f32 v7, v0, v1
	s_and_b64 vcc, exec, s[36:37]
	s_mov_b32 s52, s14
	s_mov_b32 s38, s24
	s_mov_b64 s[42:43], s[30:31]
	s_mov_b64 s[40:41], s[28:29]
	global_store_dwordx4 v[16:17], v[4:7], off
	s_cbranch_vccz .LBB0_112
	s_waitcnt vmcnt(0)
	s_cmpk_gt_u32 s18, 0xff
	s_cbranch_scc1 .LBB0_119
	s_barrier
